# P6 EpiOut epilogue hand-written: 16 residual-x loads prefetched up front + rolling prefetch with counted vmcnt (was 16 serialized round trips); HID lane-linear 16x32 block layout
# speedup vs baseline: 1.0155x; 1.0017x over previous
; __device__ __forceinline__ u32x4 pack8(const f32x4 a, const f32x4 b) { u32x4 w; w.x = cvt_pk_bf16(a[0], a[1]); w.y = cvt_pk_bf16(a[2], a[3]); w.z = cvt_pk_bf16(b[0], b[1]); w.w = cvt_pk_bf16(b[2], b[3]); return w; }
;     __device__ __forceinline__ void operator()(AccRef acc, const Unit& u, int wr, int wc, int fr, int fq) const {
;         const float* xb = (u.pm < 128) ? xp : xs - (size_t)NPROMPT * D;
; #pragma unroll
;         for (int ai = 0; ai < 2; ++ai)
; #pragma unroll
;             for (int m = 0; m < 4; ++m) { const int row = u.pm * 256 + ai * 128 + wr * 64 + m * 16 + fr; float sq = 0.f;
; #pragma unroll
;                 for (int bj = 0; bj < 2; ++bj) { const size_t off = (size_t)row * D + u.pn * 256 + bj * 128 + wc * 32 + 8 * fq;
;                     const f32x4 a0 = *(const f32x4*)(xb + off) + acc[ai][bj][m][0], a1 = *(const f32x4*)(xb + off + 4) + acc[ai][bj][m][1];
;                     *(u32x4*)(X1B + off) = pack8(a0, a1);
;                     sq += (a0[0] * a0[0] + a0[1] * a0[1]) + (a0[2] * a0[2] + a0[3] * a0[3]) + (a1[0] * a1[0] + a1[1] * a1[1]) + (a1[2] * a1[2] + a1[3] * a1[3]); }
;                 sq += __shfl_xor(sq, 16); sq += __shfl_xor(sq, 32);
;                 if (fq == 0) atomicAdd(ssq + row, sq); }
.LBB0_727:
	s_cmpk_lt_i32 s38, 0x80
	s_cselect_b32 s63, s37, s70
	s_cselect_b32 s62, s36, s47
	v_lshl_add_u32 v148, s38, 8, v158
	s_lshl_b32 s2, s60, 8
	s_ashr_i32 s34, s2, 31
	v_ashrrev_i32_e32 v149, 31, v148
	v_mov_b32_e32 v147, s34
	v_or_b32_e32 v146, s2, v144
	v_lshlrev_b64 v[170:171], 11, v[148:149]
	v_lshl_add_u64 v[170:171], v[170:171], 0, v[146:147]
	v_lshl_add_u64 v[162:163], v[170:171], 2, s[62:63]
	v_lshlrev_b64 v[170:171], 1, v[170:171]
	v_lshl_add_u64 v[164:165], s[14:15], 0, v[170:171]
	v_lshl_add_u64 v[166:167], v[148:149], 2, s[30:31]
	v_xor_b32_e32 v168, 16, v157
	v_xor_b32_e32 v169, 32, v157
	v_lshlrev_b32_e32 v168, 2, v168
	v_lshlrev_b32_e32 v169, 2, v169
	global_load_dwordx4 v[178:181], v[162:163], off
	global_load_dwordx4 v[182:185], v[162:163], off offset:16
	global_load_dwordx4 v[186:189], v[162:163], off offset:512
	global_load_dwordx4 v[190:193], v[162:163], off offset:528
	s_mov_b64 s[98:99], 0x20000
	v_lshl_add_u64 v[162:163], v[162:163], 0, s[98:99]
	global_load_dwordx4 v[194:197], v[162:163], off
	global_load_dwordx4 v[198:201], v[162:163], off offset:16
	global_load_dwordx4 v[202:205], v[162:163], off offset:512
	global_load_dwordx4 v[206:209], v[162:163], off offset:528
	s_mov_b64 s[98:99], 0x20000
	v_lshl_add_u64 v[162:163], v[162:163], 0, s[98:99]
	global_load_dwordx4 v[210:213], v[162:163], off
	global_load_dwordx4 v[214:217], v[162:163], off offset:16
	global_load_dwordx4 v[218:221], v[162:163], off offset:512
	global_load_dwordx4 v[222:225], v[162:163], off offset:528
	s_mov_b64 s[98:99], 0x20000
	v_lshl_add_u64 v[162:163], v[162:163], 0, s[98:99]
	global_load_dwordx4 v[226:229], v[162:163], off
	global_load_dwordx4 v[230:233], v[162:163], off offset:16
	global_load_dwordx4 v[234:237], v[162:163], off offset:512
	global_load_dwordx4 v[238:241], v[162:163], off offset:528
	s_mov_b64 s[98:99], 0xa0000
	v_lshl_add_u64 v[162:163], v[162:163], 0, s[98:99]
	s_waitcnt vmcnt(12)
	v_pk_add_f32 v[124:125], v[124:125], v[178:179]
	v_pk_add_f32 v[126:127], v[126:127], v[180:181]
	v_pk_add_f32 v[120:121], v[120:121], v[182:183]
	v_pk_add_f32 v[122:123], v[122:123], v[184:185]
	v_cvt_pk_bf16_f32 v172, v124, v125
	v_cvt_pk_bf16_f32 v173, v126, v127
	v_cvt_pk_bf16_f32 v174, v120, v121
	v_cvt_pk_bf16_f32 v175, v122, v123
	global_store_dwordx4 v[164:165], v[172:175], off
	v_mul_f32_e32 v125, v125, v125
	v_fmac_f32_e32 v125, v124, v124
	v_mul_f32_e32 v127, v127, v127
	v_fmac_f32_e32 v127, v126, v126
	v_mul_f32_e32 v121, v121, v121
	v_fmac_f32_e32 v121, v120, v120
	v_mul_f32_e32 v123, v123, v123
	v_fmac_f32_e32 v123, v122, v122
	v_add_f32_e32 v124, v125, v127
	v_add_f32_e32 v124, v124, v121
	v_add_f32_e32 v124, v123, v124
	v_pk_add_f32 v[116:117], v[116:117], v[186:187]
	v_pk_add_f32 v[118:119], v[118:119], v[188:189]
	v_pk_add_f32 v[112:113], v[112:113], v[190:191]
	v_pk_add_f32 v[114:115], v[114:115], v[192:193]
	v_cvt_pk_bf16_f32 v172, v116, v117
	v_cvt_pk_bf16_f32 v173, v118, v119
	v_cvt_pk_bf16_f32 v174, v112, v113
	v_cvt_pk_bf16_f32 v175, v114, v115
	global_store_dwordx4 v[164:165], v[172:175], off offset:256
	v_mul_f32_e32 v117, v117, v117
	v_fmac_f32_e32 v117, v116, v116
	v_mul_f32_e32 v119, v119, v119
	v_fmac_f32_e32 v119, v118, v118
	v_mul_f32_e32 v113, v113, v113
	v_fmac_f32_e32 v113, v112, v112
	v_mul_f32_e32 v115, v115, v115
	v_fmac_f32_e32 v115, v114, v114
	v_add_f32_e32 v116, v117, v119
	v_add_f32_e32 v116, v116, v113
	v_add_f32_e32 v116, v115, v116
	v_add_f32_e32 v170, v124, v116
	ds_bpermute_b32 v171, v168, v170
	s_waitcnt lgkmcnt(0)
	v_add_f32_e32 v170, v170, v171
	ds_bpermute_b32 v171, v169, v170
	s_mov_b64 s[100:101], 0x10000
	v_lshl_add_u64 v[164:165], v[164:165], 0, s[100:101]
	s_and_saveexec_b64 s[34:35], s[0:1]
	s_waitcnt lgkmcnt(0)
	v_add_f32_e32 v170, v170, v171
	global_atomic_add_f32 v[166:167], v170, off
	s_or_b64 exec, exec, s[34:35]
	global_load_dwordx4 v[178:181], v[162:163], off
	global_load_dwordx4 v[182:185], v[162:163], off offset:16
	global_load_dwordx4 v[186:189], v[162:163], off offset:512
	global_load_dwordx4 v[190:193], v[162:163], off offset:528
	s_mov_b64 s[98:99], 0x20000
	v_lshl_add_u64 v[162:163], v[162:163], 0, s[98:99]
	s_waitcnt vmcnt(15)
	v_pk_add_f32 v[108:109], v[108:109], v[194:195]
	v_pk_add_f32 v[110:111], v[110:111], v[196:197]
	v_pk_add_f32 v[104:105], v[104:105], v[198:199]
	v_pk_add_f32 v[106:107], v[106:107], v[200:201]
	v_cvt_pk_bf16_f32 v172, v108, v109
	v_cvt_pk_bf16_f32 v173, v110, v111
	v_cvt_pk_bf16_f32 v174, v104, v105
	v_cvt_pk_bf16_f32 v175, v106, v107
	global_store_dwordx4 v[164:165], v[172:175], off
	v_mul_f32_e32 v109, v109, v109
	v_fmac_f32_e32 v109, v108, v108
	v_mul_f32_e32 v111, v111, v111
	v_fmac_f32_e32 v111, v110, v110
	v_mul_f32_e32 v105, v105, v105
	v_fmac_f32_e32 v105, v104, v104
	v_mul_f32_e32 v107, v107, v107
	v_fmac_f32_e32 v107, v106, v106
	v_add_f32_e32 v108, v109, v111
	v_add_f32_e32 v108, v108, v105
	v_add_f32_e32 v108, v107, v108
	v_pk_add_f32 v[100:101], v[100:101], v[202:203]
	v_pk_add_f32 v[102:103], v[102:103], v[204:205]
	v_pk_add_f32 v[96:97], v[96:97], v[206:207]
	v_pk_add_f32 v[98:99], v[98:99], v[208:209]
	v_cvt_pk_bf16_f32 v172, v100, v101
	v_cvt_pk_bf16_f32 v173, v102, v103
	v_cvt_pk_bf16_f32 v174, v96, v97
	v_cvt_pk_bf16_f32 v175, v98, v99
	global_store_dwordx4 v[164:165], v[172:175], off offset:256
	v_mul_f32_e32 v101, v101, v101
	v_fmac_f32_e32 v101, v100, v100
	v_mul_f32_e32 v103, v103, v103
	v_fmac_f32_e32 v103, v102, v102
	v_mul_f32_e32 v97, v97, v97
	v_fmac_f32_e32 v97, v96, v96
	v_mul_f32_e32 v99, v99, v99
	v_fmac_f32_e32 v99, v98, v98
	v_add_f32_e32 v100, v101, v103
	v_add_f32_e32 v100, v100, v97
	v_add_f32_e32 v100, v99, v100
	v_add_f32_e32 v170, v108, v100
	ds_bpermute_b32 v171, v168, v170
	s_waitcnt lgkmcnt(0)
; __device__ __forceinline__ u32x4 pack8(const f32x4 a, const f32x4 b) { u32x4 w; w.x = cvt_pk_bf16(a[0], a[1]); w.y = cvt_pk_bf16(a[2], a[3]); w.z = cvt_pk_bf16(b[0], b[1]); w.w = cvt_pk_bf16(b[2], b[3]); return w; }
;     __device__ __forceinline__ void operator()(AccRef acc, const Unit& u, int wr, int wc, int fr, int fq) const {
;     ...
;         for (int ai = 0; ai < 2; ++ai)
; #pragma unroll
;             for (int m = 0; m < 4; ++m) { const int row = u.pm * 256 + ai * 128 + wr * 64 + m * 16 + fr; float sq = 0.f;
; #pragma unroll
;                 for (int bj = 0; bj < 2; ++bj) { const size_t off = (size_t)row * D + u.pn * 256 + bj * 128 + wc * 32 + 8 * fq;
;                     const f32x4 a0 = *(const f32x4*)(xb + off) + acc[ai][bj][m][0], a1 = *(const f32x4*)(xb + off + 4) + acc[ai][bj][m][1];
;                     *(u32x4*)(X1B + off) = pack8(a0, a1);
;                     sq += (a0[0] * a0[0] + a0[1] * a0[1]) + (a0[2] * a0[2] + a0[3] * a0[3]) + (a1[0] * a1[0] + a1[1] * a1[1]) + (a1[2] * a1[2] + a1[3] * a1[3]); }
;                 sq += __shfl_xor(sq, 16); sq += __shfl_xor(sq, 32);
;                 if (fq == 0) atomicAdd(ssq + row, sq); }
	v_add_f32_e32 v170, v170, v171
	ds_bpermute_b32 v171, v169, v170
	s_mov_b64 s[100:101], 0x10000
	v_lshl_add_u64 v[164:165], v[164:165], 0, s[100:101]
	s_and_saveexec_b64 s[34:35], s[0:1]
	s_waitcnt lgkmcnt(0)
	v_add_f32_e32 v170, v170, v171
	global_atomic_add_f32 v[166:167], v170, off offset:64
	s_or_b64 exec, exec, s[34:35]
	global_load_dwordx4 v[194:197], v[162:163], off
	global_load_dwordx4 v[198:201], v[162:163], off offset:16
	global_load_dwordx4 v[202:205], v[162:163], off offset:512
	global_load_dwordx4 v[206:209], v[162:163], off offset:528
	s_mov_b64 s[98:99], 0x20000
	v_lshl_add_u64 v[162:163], v[162:163], 0, s[98:99]
	s_waitcnt vmcnt(18)
	v_pk_add_f32 v[92:93], v[92:93], v[210:211]
	v_pk_add_f32 v[94:95], v[94:95], v[212:213]
	v_pk_add_f32 v[88:89], v[88:89], v[214:215]
	v_pk_add_f32 v[90:91], v[90:91], v[216:217]
	v_cvt_pk_bf16_f32 v172, v92, v93
	v_cvt_pk_bf16_f32 v173, v94, v95
	v_cvt_pk_bf16_f32 v174, v88, v89
	v_cvt_pk_bf16_f32 v175, v90, v91
	global_store_dwordx4 v[164:165], v[172:175], off
	v_mul_f32_e32 v93, v93, v93
	v_fmac_f32_e32 v93, v92, v92
	v_mul_f32_e32 v95, v95, v95
	v_fmac_f32_e32 v95, v94, v94
	v_mul_f32_e32 v89, v89, v89
	v_fmac_f32_e32 v89, v88, v88
	v_mul_f32_e32 v91, v91, v91
	v_fmac_f32_e32 v91, v90, v90
	v_add_f32_e32 v92, v93, v95
	v_add_f32_e32 v92, v92, v89
	v_add_f32_e32 v92, v91, v92
	v_pk_add_f32 v[84:85], v[84:85], v[218:219]
	v_pk_add_f32 v[86:87], v[86:87], v[220:221]
	v_pk_add_f32 v[80:81], v[80:81], v[222:223]
	v_pk_add_f32 v[82:83], v[82:83], v[224:225]
	v_cvt_pk_bf16_f32 v172, v84, v85
	v_cvt_pk_bf16_f32 v173, v86, v87
	v_cvt_pk_bf16_f32 v174, v80, v81
	v_cvt_pk_bf16_f32 v175, v82, v83
	global_store_dwordx4 v[164:165], v[172:175], off offset:256
	v_mul_f32_e32 v85, v85, v85
	v_fmac_f32_e32 v85, v84, v84
	v_mul_f32_e32 v87, v87, v87
	v_fmac_f32_e32 v87, v86, v86
	v_mul_f32_e32 v81, v81, v81
	v_fmac_f32_e32 v81, v80, v80
	v_mul_f32_e32 v83, v83, v83
	v_fmac_f32_e32 v83, v82, v82
	v_add_f32_e32 v84, v85, v87
	v_add_f32_e32 v84, v84, v81
	v_add_f32_e32 v84, v83, v84
	v_add_f32_e32 v170, v92, v84
	ds_bpermute_b32 v171, v168, v170
	s_waitcnt lgkmcnt(0)
	v_add_f32_e32 v170, v170, v171
	ds_bpermute_b32 v171, v169, v170
	s_mov_b64 s[100:101], 0x10000
	v_lshl_add_u64 v[164:165], v[164:165], 0, s[100:101]
	s_and_saveexec_b64 s[34:35], s[0:1]
	s_waitcnt lgkmcnt(0)
	v_add_f32_e32 v170, v170, v171
	global_atomic_add_f32 v[166:167], v170, off offset:128
	s_or_b64 exec, exec, s[34:35]
	global_load_dwordx4 v[210:213], v[162:163], off
	global_load_dwordx4 v[214:217], v[162:163], off offset:16
	global_load_dwordx4 v[218:221], v[162:163], off offset:512
	global_load_dwordx4 v[222:225], v[162:163], off offset:528
	s_mov_b64 s[98:99], 0x20000
	v_lshl_add_u64 v[162:163], v[162:163], 0, s[98:99]
	s_waitcnt vmcnt(21)
	v_pk_add_f32 v[76:77], v[76:77], v[226:227]
	v_pk_add_f32 v[78:79], v[78:79], v[228:229]
	v_pk_add_f32 v[72:73], v[72:73], v[230:231]
	v_pk_add_f32 v[74:75], v[74:75], v[232:233]
	v_cvt_pk_bf16_f32 v172, v76, v77
	v_cvt_pk_bf16_f32 v173, v78, v79
	v_cvt_pk_bf16_f32 v174, v72, v73
	v_cvt_pk_bf16_f32 v175, v74, v75
	global_store_dwordx4 v[164:165], v[172:175], off
	v_mul_f32_e32 v77, v77, v77
	v_fmac_f32_e32 v77, v76, v76
	v_mul_f32_e32 v79, v79, v79
	v_fmac_f32_e32 v79, v78, v78
	v_mul_f32_e32 v73, v73, v73
	v_fmac_f32_e32 v73, v72, v72
	v_mul_f32_e32 v75, v75, v75
	v_fmac_f32_e32 v75, v74, v74
	v_add_f32_e32 v76, v77, v79
	v_add_f32_e32 v76, v76, v73
	v_add_f32_e32 v76, v75, v76
	v_pk_add_f32 v[68:69], v[68:69], v[234:235]
	v_pk_add_f32 v[70:71], v[70:71], v[236:237]
	v_pk_add_f32 v[64:65], v[64:65], v[238:239]
	v_pk_add_f32 v[66:67], v[66:67], v[240:241]
	v_cvt_pk_bf16_f32 v172, v68, v69
	v_cvt_pk_bf16_f32 v173, v70, v71
	v_cvt_pk_bf16_f32 v174, v64, v65
	v_cvt_pk_bf16_f32 v175, v66, v67
	global_store_dwordx4 v[164:165], v[172:175], off offset:256
	v_mul_f32_e32 v69, v69, v69
	v_fmac_f32_e32 v69, v68, v68
	v_mul_f32_e32 v71, v71, v71
	v_fmac_f32_e32 v71, v70, v70
	v_mul_f32_e32 v65, v65, v65
	v_fmac_f32_e32 v65, v64, v64
	v_mul_f32_e32 v67, v67, v67
	v_fmac_f32_e32 v67, v66, v66
	v_add_f32_e32 v68, v69, v71
	v_add_f32_e32 v68, v68, v65
	v_add_f32_e32 v68, v67, v68
	v_add_f32_e32 v170, v76, v68
	ds_bpermute_b32 v171, v168, v170
	s_waitcnt lgkmcnt(0)
	v_add_f32_e32 v170, v170, v171
	ds_bpermute_b32 v171, v169, v170
	s_mov_b64 s[100:101], 0x50000
	v_lshl_add_u64 v[164:165], v[164:165], 0, s[100:101]
	s_and_saveexec_b64 s[34:35], s[0:1]
	s_waitcnt lgkmcnt(0)
	v_add_f32_e32 v170, v170, v171
	global_atomic_add_f32 v[166:167], v170, off offset:192
	s_or_b64 exec, exec, s[34:35]
	global_load_dwordx4 v[226:229], v[162:163], off
	global_load_dwordx4 v[230:233], v[162:163], off offset:16
	global_load_dwordx4 v[234:237], v[162:163], off offset:512
	global_load_dwordx4 v[238:241], v[162:163], off offset:528
	s_waitcnt vmcnt(21)
	v_pk_add_f32 v[60:61], v[60:61], v[178:179]
	v_pk_add_f32 v[62:63], v[62:63], v[180:181]
	v_pk_add_f32 v[56:57], v[56:57], v[182:183]
	v_pk_add_f32 v[58:59], v[58:59], v[184:185]
	v_cvt_pk_bf16_f32 v172, v60, v61
	v_cvt_pk_bf16_f32 v173, v62, v63
	v_cvt_pk_bf16_f32 v174, v56, v57
	v_cvt_pk_bf16_f32 v175, v58, v59
	global_store_dwordx4 v[164:165], v[172:175], off
	v_mul_f32_e32 v61, v61, v61
	v_fmac_f32_e32 v61, v60, v60
	v_mul_f32_e32 v63, v63, v63
	v_fmac_f32_e32 v63, v62, v62
	v_mul_f32_e32 v57, v57, v57
	v_fmac_f32_e32 v57, v56, v56
	v_mul_f32_e32 v59, v59, v59
	v_fmac_f32_e32 v59, v58, v58
	v_add_f32_e32 v60, v61, v63
	v_add_f32_e32 v60, v60, v57
	v_add_f32_e32 v60, v59, v60
	v_pk_add_f32 v[52:53], v[52:53], v[186:187]
	v_pk_add_f32 v[54:55], v[54:55], v[188:189]
	v_pk_add_f32 v[48:49], v[48:49], v[190:191]
	v_pk_add_f32 v[50:51], v[50:51], v[192:193]
	v_cvt_pk_bf16_f32 v172, v52, v53
	v_cvt_pk_bf16_f32 v173, v54, v55
	v_cvt_pk_bf16_f32 v174, v48, v49
	v_cvt_pk_bf16_f32 v175, v50, v51
	global_store_dwordx4 v[164:165], v[172:175], off offset:256
	v_mul_f32_e32 v53, v53, v53
	v_fmac_f32_e32 v53, v52, v52
	v_mul_f32_e32 v55, v55, v55
	v_fmac_f32_e32 v55, v54, v54
	v_mul_f32_e32 v49, v49, v49
	v_fmac_f32_e32 v49, v48, v48
	v_mul_f32_e32 v51, v51, v51
	v_fmac_f32_e32 v51, v50, v50
	v_add_f32_e32 v52, v53, v55
	v_add_f32_e32 v52, v52, v49
	v_add_f32_e32 v52, v51, v52
	v_add_f32_e32 v170, v60, v52
	ds_bpermute_b32 v171, v168, v170
	s_waitcnt lgkmcnt(0)
; __device__ __forceinline__ u32x4 pack8(const f32x4 a, const f32x4 b) { u32x4 w; w.x = cvt_pk_bf16(a[0], a[1]); w.y = cvt_pk_bf16(a[2], a[3]); w.z = cvt_pk_bf16(b[0], b[1]); w.w = cvt_pk_bf16(b[2], b[3]); return w; }
;     __device__ __forceinline__ void operator()(AccRef acc, const Unit& u, int wr, int wc, int fr, int fq) const {
;     ...
;         for (int ai = 0; ai < 2; ++ai)
; #pragma unroll
;             for (int m = 0; m < 4; ++m) { const int row = u.pm * 256 + ai * 128 + wr * 64 + m * 16 + fr; float sq = 0.f;
; #pragma unroll
;                 for (int bj = 0; bj < 2; ++bj) { const size_t off = (size_t)row * D + u.pn * 256 + bj * 128 + wc * 32 + 8 * fq;
;                     const f32x4 a0 = *(const f32x4*)(xb + off) + acc[ai][bj][m][0], a1 = *(const f32x4*)(xb + off + 4) + acc[ai][bj][m][1];
;                     *(u32x4*)(X1B + off) = pack8(a0, a1);
;                     sq += (a0[0] * a0[0] + a0[1] * a0[1]) + (a0[2] * a0[2] + a0[3] * a0[3]) + (a1[0] * a1[0] + a1[1] * a1[1]) + (a1[2] * a1[2] + a1[3] * a1[3]); }
;                 sq += __shfl_xor(sq, 16); sq += __shfl_xor(sq, 32);
;                 if (fq == 0) atomicAdd(ssq + row, sq); }
;         if (u.pm >= 128) {
;             asm volatile("s_waitcnt vmcnt(0)" ::: "memory"); __builtin_amdgcn_fence(__ATOMIC_RELEASE, "agent"); asm volatile("s_waitcnt vmcnt(0)" ::: "memory");
;             if (fr + 16 * fq == 0) __hip_atomic_fetch_add(flag, 1u, __ATOMIC_RELAXED, __HIP_MEMORY_SCOPE_AGENT); }
	v_add_f32_e32 v170, v170, v171
	ds_bpermute_b32 v171, v169, v170
	s_mov_b64 s[100:101], 0x10000
	v_lshl_add_u64 v[164:165], v[164:165], 0, s[100:101]
	s_and_saveexec_b64 s[34:35], s[0:1]
	s_waitcnt lgkmcnt(0)
	v_add_f32_e32 v170, v170, v171
	global_atomic_add_f32 v[166:167], v170, off offset:512
	s_or_b64 exec, exec, s[34:35]
	s_waitcnt vmcnt(17)
	v_pk_add_f32 v[44:45], v[44:45], v[194:195]
	v_pk_add_f32 v[46:47], v[46:47], v[196:197]
	v_pk_add_f32 v[40:41], v[40:41], v[198:199]
	v_pk_add_f32 v[42:43], v[42:43], v[200:201]
	v_cvt_pk_bf16_f32 v172, v44, v45
	v_cvt_pk_bf16_f32 v173, v46, v47
	v_cvt_pk_bf16_f32 v174, v40, v41
	v_cvt_pk_bf16_f32 v175, v42, v43
	global_store_dwordx4 v[164:165], v[172:175], off
	v_mul_f32_e32 v45, v45, v45
	v_fmac_f32_e32 v45, v44, v44
	v_mul_f32_e32 v47, v47, v47
	v_fmac_f32_e32 v47, v46, v46
	v_mul_f32_e32 v41, v41, v41
	v_fmac_f32_e32 v41, v40, v40
	v_mul_f32_e32 v43, v43, v43
	v_fmac_f32_e32 v43, v42, v42
	v_add_f32_e32 v44, v45, v47
	v_add_f32_e32 v44, v44, v41
	v_add_f32_e32 v44, v43, v44
	v_pk_add_f32 v[36:37], v[36:37], v[202:203]
	v_pk_add_f32 v[38:39], v[38:39], v[204:205]
	v_pk_add_f32 v[32:33], v[32:33], v[206:207]
	v_pk_add_f32 v[34:35], v[34:35], v[208:209]
	v_cvt_pk_bf16_f32 v172, v36, v37
	v_cvt_pk_bf16_f32 v173, v38, v39
	v_cvt_pk_bf16_f32 v174, v32, v33
	v_cvt_pk_bf16_f32 v175, v34, v35
	global_store_dwordx4 v[164:165], v[172:175], off offset:256
	v_mul_f32_e32 v37, v37, v37
	v_fmac_f32_e32 v37, v36, v36
	v_mul_f32_e32 v39, v39, v39
	v_fmac_f32_e32 v39, v38, v38
	v_mul_f32_e32 v33, v33, v33
	v_fmac_f32_e32 v33, v32, v32
	v_mul_f32_e32 v35, v35, v35
	v_fmac_f32_e32 v35, v34, v34
	v_add_f32_e32 v36, v37, v39
	v_add_f32_e32 v36, v36, v33
	v_add_f32_e32 v36, v35, v36
	v_add_f32_e32 v170, v44, v36
	ds_bpermute_b32 v171, v168, v170
	s_waitcnt lgkmcnt(0)
	v_add_f32_e32 v170, v170, v171
	ds_bpermute_b32 v171, v169, v170
	s_mov_b64 s[100:101], 0x10000
	v_lshl_add_u64 v[164:165], v[164:165], 0, s[100:101]
	s_and_saveexec_b64 s[34:35], s[0:1]
	s_waitcnt lgkmcnt(0)
	v_add_f32_e32 v170, v170, v171
	global_atomic_add_f32 v[166:167], v170, off offset:576
	s_or_b64 exec, exec, s[34:35]
	s_waitcnt vmcnt(13)
	v_pk_add_f32 v[28:29], v[28:29], v[210:211]
	v_pk_add_f32 v[30:31], v[30:31], v[212:213]
	v_pk_add_f32 v[24:25], v[24:25], v[214:215]
	v_pk_add_f32 v[26:27], v[26:27], v[216:217]
	v_cvt_pk_bf16_f32 v172, v28, v29
	v_cvt_pk_bf16_f32 v173, v30, v31
	v_cvt_pk_bf16_f32 v174, v24, v25
	v_cvt_pk_bf16_f32 v175, v26, v27
	global_store_dwordx4 v[164:165], v[172:175], off
	v_mul_f32_e32 v29, v29, v29
	v_fmac_f32_e32 v29, v28, v28
	v_mul_f32_e32 v31, v31, v31
	v_fmac_f32_e32 v31, v30, v30
	v_mul_f32_e32 v25, v25, v25
	v_fmac_f32_e32 v25, v24, v24
	v_mul_f32_e32 v27, v27, v27
	v_fmac_f32_e32 v27, v26, v26
	v_add_f32_e32 v28, v29, v31
	v_add_f32_e32 v28, v28, v25
	v_add_f32_e32 v28, v27, v28
	v_pk_add_f32 v[20:21], v[20:21], v[218:219]
	v_pk_add_f32 v[22:23], v[22:23], v[220:221]
	v_pk_add_f32 v[16:17], v[16:17], v[222:223]
	v_pk_add_f32 v[18:19], v[18:19], v[224:225]
	v_cvt_pk_bf16_f32 v172, v20, v21
	v_cvt_pk_bf16_f32 v173, v22, v23
	v_cvt_pk_bf16_f32 v174, v16, v17
	v_cvt_pk_bf16_f32 v175, v18, v19
	global_store_dwordx4 v[164:165], v[172:175], off offset:256
	v_mul_f32_e32 v21, v21, v21
	v_fmac_f32_e32 v21, v20, v20
	v_mul_f32_e32 v23, v23, v23
	v_fmac_f32_e32 v23, v22, v22
	v_mul_f32_e32 v17, v17, v17
	v_fmac_f32_e32 v17, v16, v16
	v_mul_f32_e32 v19, v19, v19
	v_fmac_f32_e32 v19, v18, v18
	v_add_f32_e32 v20, v21, v23
	v_add_f32_e32 v20, v20, v17
	v_add_f32_e32 v20, v19, v20
	v_add_f32_e32 v170, v28, v20
	ds_bpermute_b32 v171, v168, v170
	s_waitcnt lgkmcnt(0)
	v_add_f32_e32 v170, v170, v171
	ds_bpermute_b32 v171, v169, v170
	s_mov_b64 s[100:101], 0x10000
	v_lshl_add_u64 v[164:165], v[164:165], 0, s[100:101]
	s_and_saveexec_b64 s[34:35], s[0:1]
	s_waitcnt lgkmcnt(0)
	v_add_f32_e32 v170, v170, v171
	global_atomic_add_f32 v[166:167], v170, off offset:640
	s_or_b64 exec, exec, s[34:35]
	s_waitcnt vmcnt(9)
	v_pk_add_f32 v[12:13], v[12:13], v[226:227]
	v_pk_add_f32 v[14:15], v[14:15], v[228:229]
	v_pk_add_f32 v[8:9], v[8:9], v[230:231]
	v_pk_add_f32 v[10:11], v[10:11], v[232:233]
	v_cvt_pk_bf16_f32 v172, v12, v13
	v_cvt_pk_bf16_f32 v173, v14, v15
	v_cvt_pk_bf16_f32 v174, v8, v9
	v_cvt_pk_bf16_f32 v175, v10, v11
	global_store_dwordx4 v[164:165], v[172:175], off
	v_mul_f32_e32 v13, v13, v13
	v_fmac_f32_e32 v13, v12, v12
	v_mul_f32_e32 v15, v15, v15
	v_fmac_f32_e32 v15, v14, v14
	v_mul_f32_e32 v9, v9, v9
	v_fmac_f32_e32 v9, v8, v8
	v_mul_f32_e32 v11, v11, v11
	v_fmac_f32_e32 v11, v10, v10
	v_add_f32_e32 v12, v13, v15
	v_add_f32_e32 v12, v12, v9
	v_add_f32_e32 v12, v11, v12
	v_pk_add_f32 v[4:5], v[4:5], v[234:235]
	v_pk_add_f32 v[6:7], v[6:7], v[236:237]
	v_pk_add_f32 v[0:1], v[0:1], v[238:239]
	v_pk_add_f32 v[2:3], v[2:3], v[240:241]
	v_cvt_pk_bf16_f32 v172, v4, v5
	v_cvt_pk_bf16_f32 v173, v6, v7
	v_cvt_pk_bf16_f32 v174, v0, v1
	v_cvt_pk_bf16_f32 v175, v2, v3
	global_store_dwordx4 v[164:165], v[172:175], off offset:256
	v_mul_f32_e32 v5, v5, v5
	v_fmac_f32_e32 v5, v4, v4
	v_mul_f32_e32 v7, v7, v7
	v_fmac_f32_e32 v7, v6, v6
	v_mul_f32_e32 v1, v1, v1
	v_fmac_f32_e32 v1, v0, v0
	v_mul_f32_e32 v3, v3, v3
	v_fmac_f32_e32 v3, v2, v2
	v_add_f32_e32 v4, v5, v7
	v_add_f32_e32 v4, v4, v1
	v_add_f32_e32 v4, v3, v4
	v_add_f32_e32 v170, v12, v4
	ds_bpermute_b32 v171, v168, v170
	s_waitcnt lgkmcnt(0)
	v_add_f32_e32 v170, v170, v171
	ds_bpermute_b32 v171, v169, v170
	s_and_saveexec_b64 s[34:35], s[0:1]
	s_waitcnt lgkmcnt(0)
	v_add_f32_e32 v170, v170, v171
	global_atomic_add_f32 v[166:167], v170, off offset:704
	s_or_b64 exec, exec, s[34:35]
	s_cmpk_lt_i32 s38, 0x80
	s_cbranch_scc0 .LBB0_745
.LBB0_743:
	s_andn2_b64 vcc, exec, s[54:55]
	s_mov_b64 s[34:35], -1
	s_cbranch_vccnz .LBB0_714
	s_branch .LBB0_749
.LBB0_745:
	s_waitcnt vmcnt(0)
	buffer_wbl2 sc1
	s_waitcnt vmcnt(0) lgkmcnt(0)
	s_waitcnt vmcnt(0)
	s_and_saveexec_b64 s[34:35], s[8:9]
	s_cbranch_execz .LBB0_748
	s_mov_b64 s[38:39], exec
	v_mbcnt_lo_u32_b32 v0, s38, 0
	v_mbcnt_hi_u32_b32 v0, s39, v0
	v_cmp_eq_u32_e32 vcc, 0, v0
	s_and_b64 s[48:49], exec, vcc
	s_mov_b64 exec, s[48:49]
	s_cbranch_execz .LBB0_748
	s_bcnt1_i32_b64 s2, s[38:39]
	v_mov_b32_e32 v0, s2
	global_atomic_add v131, v0, s[12:13]

; __device__ __forceinline__ u32x4 pack8(const f32x4 a, const f32x4 b) { u32x4 w; w.x = cvt_pk_bf16(a[0], a[1]); w.y = cvt_pk_bf16(a[2], a[3]); w.z = cvt_pk_bf16(b[0], b[1]); w.w = cvt_pk_bf16(b[2], b[3]); return w; }
;     __device__ __forceinline__ void operator()(AccRef acc, const Unit& u, int wr, int wc, int fr, int fq) const {
; #pragma unroll
;         for (int ai = 0; ai < 2; ++ai)
; #pragma unroll
;             for (int m = 0; m < 4; ++m) { const int row = u.pm * 256 + ai * 128 + wr * 64 + m * 16 + fr;
;                 const float r2 = rsqrtf(ssq[row] * (1.0f / D) + EPS);
; #pragma unroll
;                 for (int bj = 0; bj < 2; ++bj) { const int col = u.pn * 256 + bj * 128 + wc * 32 + 8 * fq;
;                     f32x4 h0 = acc[ai][bj][m][0] * r2, h1 = acc[ai][bj][m][1] * r2;
; #pragma unroll
;                     for (int q = 0; q < 4; ++q) { const float a = fmaxf(h0[q], 0.f), b = fmaxf(h1[q], 0.f); h0[q] = a * a; h1[q] = b * b; }
;                     __builtin_nontemporal_store(pack8(h0, h1), (u32x4*)(HID + (size_t)row * DFF + col)); } }
;     }
.LBB0_764:
	v_lshl_add_u32 v128, s4, 8, v142
	v_mov_b32_e32 v129, 0
	v_lshl_add_u64 v[132:133], v[128:129], 2, s[30:31]
	v_and_b32_e32 v128, -16, v128
	global_load_dword v130, v[132:133], off
	v_mov_b32_e32 v134, 0x358637bd
	s_mov_b32 s0, 0x800000
	v_lshl_or_b32 v131, s2, 8, v137
	v_or_b32_e32 v135, s23, v131
	v_readlane_b32 s4, v242, 6
	v_lshlrev_b64 v[138:139], 14, v[128:129]
	v_readlane_b32 s5, v242, 7
	v_mov_b32_e32 v131, v129
	s_waitcnt vmcnt(0)
	v_fmamk_f32 v130, v130, 0x3a000000, v134
	v_mul_f32_e32 v137, 0x4b800000, v130
	v_cmp_gt_f32_e32 vcc, s0, v130
	v_lshl_add_u64 v[138:139], s[4:5], 0, v[138:139]
	s_nop 0
	v_cndmask_b32_e32 v130, v130, v137, vcc
	v_rsq_f32_e32 v137, v130
	v_lshrrev_b32_e32 v130, 5, v135
	v_lshlrev_b32_e32 v130, 10, v130
	v_and_b32_e32 v135, 63, v136
	v_lshl_add_u32 v130, v135, 4, v130
	v_add_u32_e32 v130, 0x1000, v130
	v_lshl_add_u64 v[138:139], v[138:139], 0, v[130:131]
	v_mul_f32_e32 v135, 0x45800000, v137
	v_cndmask_b32_e32 v140, v137, v135, vcc
	v_pk_mul_f32 v[126:127], v[126:127], v[140:141] op_sel_hi:[1,0]
	v_pk_mul_f32 v[124:125], v[124:125], v[140:141] op_sel_hi:[1,0]
	v_pk_mul_f32 v[122:123], v[122:123], v[140:141] op_sel_hi:[1,0]
	v_pk_mul_f32 v[120:121], v[120:121], v[140:141] op_sel_hi:[1,0]
	v_pk_mul_f32 v[118:119], v[118:119], v[140:141] op_sel_hi:[1,0]
	v_pk_mul_f32 v[114:115], v[114:115], v[140:141] op_sel_hi:[1,0]
	v_pk_mul_f32 v[112:113], v[112:113], v[140:141] op_sel_hi:[1,0]
	v_pk_mul_f32 v[116:117], v[116:117], v[140:141] op_sel_hi:[1,0]
	v_max_f32_e32 v124, 0, v124
	v_max_f32_e32 v120, 0, v120
	v_max_f32_e32 v125, 0, v125
	v_max_f32_e32 v121, 0, v121
	v_max_f32_e32 v126, 0, v126
	v_max_f32_e32 v122, 0, v122
	v_max_f32_e32 v127, 0, v127
	v_max_f32_e32 v123, 0, v123
	v_max_f32_e32 v112, 0, v112
	v_max_f32_e32 v113, 0, v113
	v_max_f32_e32 v118, 0, v118
	v_max_f32_e32 v114, 0, v114
	v_max_f32_e32 v115, 0, v115
	v_max_f32_e32 v116, 0, v116
	v_max_f32_e32 v117, 0, v117
	v_max_f32_e32 v119, 0, v119
	v_mul_f32_e32 v124, v124, v124
	v_mul_f32_e32 v120, v120, v120
	v_mul_f32_e32 v125, v125, v125
	v_mul_f32_e32 v121, v121, v121
	v_mul_f32_e32 v126, v126, v126
	v_mul_f32_e32 v122, v122, v122
	v_mul_f32_e32 v127, v127, v127
	v_mul_f32_e32 v123, v123, v123
	v_mul_f32_e32 v135, v112, v112
	v_mul_f32_e32 v137, v113, v113
	v_mul_f32_e32 v118, v118, v118
	v_mul_f32_e32 v140, v114, v114
	v_mul_f32_e32 v141, v115, v115
	v_cvt_pk_bf16_f32 v112, v124, v125
	v_cvt_pk_bf16_f32 v113, v126, v127
	v_cvt_pk_bf16_f32 v114, v120, v121
	v_cvt_pk_bf16_f32 v115, v122, v123
	v_mul_f32_e32 v116, v116, v116
	v_mul_f32_e32 v117, v117, v117
	v_mul_f32_e32 v119, v119, v119
	global_store_dwordx4 v[138:139], v[112:115], off offset:-4096 nt
	s_nop 1
	v_cvt_pk_bf16_f32 v112, v116, v117
	v_cvt_pk_bf16_f32 v113, v118, v119
	v_cvt_pk_bf16_f32 v114, v135, v137
	v_cvt_pk_bf16_f32 v115, v140, v141
	global_load_dword v118, v[132:133], off offset:64
	v_or_b32_e32 v116, 16, v128
	global_store_dwordx4 v[138:139], v[112:115], off nt
	v_mov_b32_e32 v117, v129
	v_lshlrev_b64 v[116:117], 14, v[116:117]
	v_lshl_add_u64 v[116:117], s[4:5], 0, v[116:117]
	v_lshl_add_u64 v[116:117], v[116:117], 0, v[130:131]
	s_waitcnt vmcnt(1)
	v_fmamk_f32 v118, v118, 0x3a000000, v134
	v_mul_f32_e32 v119, 0x4b800000, v118
	v_cmp_gt_f32_e32 vcc, s0, v118
	s_nop 1
	v_cndmask_b32_e32 v118, v118, v119, vcc
	v_rsq_f32_e32 v118, v118
	s_nop 0
	v_mul_f32_e32 v112, 0x45800000, v118
	v_cndmask_b32_e32 v112, v118, v112, vcc
	v_pk_mul_f32 v[110:111], v[110:111], v[112:113] op_sel_hi:[1,0]
	v_pk_mul_f32 v[108:109], v[108:109], v[112:113] op_sel_hi:[1,0]
	v_pk_mul_f32 v[106:107], v[106:107], v[112:113] op_sel_hi:[1,0]
	v_pk_mul_f32 v[104:105], v[104:105], v[112:113] op_sel_hi:[1,0]
	v_pk_mul_f32 v[102:103], v[102:103], v[112:113] op_sel_hi:[1,0]
	v_pk_mul_f32 v[98:99], v[98:99], v[112:113] op_sel_hi:[1,0]
	v_pk_mul_f32 v[96:97], v[96:97], v[112:113] op_sel_hi:[1,0]
	v_pk_mul_f32 v[100:101], v[100:101], v[112:113] op_sel_hi:[1,0]
	v_max_f32_e32 v108, 0, v108
	v_max_f32_e32 v104, 0, v104
	v_max_f32_e32 v109, 0, v109
	v_max_f32_e32 v105, 0, v105
	v_max_f32_e32 v110, 0, v110
	v_max_f32_e32 v106, 0, v106
	v_max_f32_e32 v111, 0, v111
	v_max_f32_e32 v107, 0, v107
	v_max_f32_e32 v96, 0, v96
	v_max_f32_e32 v97, 0, v97
	v_max_f32_e32 v102, 0, v102
	v_max_f32_e32 v98, 0, v98
	v_max_f32_e32 v99, 0, v99
	v_max_f32_e32 v100, 0, v100
	v_max_f32_e32 v101, 0, v101
	v_max_f32_e32 v103, 0, v103
	v_mul_f32_e32 v108, v108, v108
	v_mul_f32_e32 v104, v104, v104
	v_mul_f32_e32 v109, v109, v109
	v_mul_f32_e32 v105, v105, v105
	v_mul_f32_e32 v110, v110, v110
	v_mul_f32_e32 v106, v106, v106
	v_mul_f32_e32 v111, v111, v111
	v_mul_f32_e32 v107, v107, v107
	v_mul_f32_e32 v112, v96, v96
	v_mul_f32_e32 v113, v97, v97
	v_mul_f32_e32 v102, v102, v102
	v_mul_f32_e32 v114, v98, v98
	v_mul_f32_e32 v115, v99, v99
	v_cvt_pk_bf16_f32 v96, v108, v109
	v_cvt_pk_bf16_f32 v97, v110, v111
	v_cvt_pk_bf16_f32 v98, v104, v105
	v_cvt_pk_bf16_f32 v99, v106, v107
	v_mul_f32_e32 v100, v100, v100
	v_mul_f32_e32 v101, v101, v101
	v_mul_f32_e32 v103, v103, v103
	global_store_dwordx4 v[116:117], v[96:99], off offset:-4096 nt
	s_nop 1
	v_cvt_pk_bf16_f32 v96, v100, v101
	v_cvt_pk_bf16_f32 v97, v102, v103
	v_cvt_pk_bf16_f32 v98, v112, v113
	v_cvt_pk_bf16_f32 v99, v114, v115
	global_load_dword v102, v[132:133], off offset:128
	v_or_b32_e32 v100, 32, v128
	global_store_dwordx4 v[116:117], v[96:99], off nt
	v_mov_b32_e32 v101, v129
	v_lshlrev_b64 v[100:101], 14, v[100:101]
	v_lshl_add_u64 v[100:101], s[4:5], 0, v[100:101]
	v_lshl_add_u64 v[100:101], v[100:101], 0, v[130:131]
	s_waitcnt vmcnt(1)
; __device__ __forceinline__ u32x4 pack8(const f32x4 a, const f32x4 b) { u32x4 w; w.x = cvt_pk_bf16(a[0], a[1]); w.y = cvt_pk_bf16(a[2], a[3]); w.z = cvt_pk_bf16(b[0], b[1]); w.w = cvt_pk_bf16(b[2], b[3]); return w; }
;     __device__ __forceinline__ void operator()(AccRef acc, const Unit& u, int wr, int wc, int fr, int fq) const {
; #pragma unroll
;         for (int ai = 0; ai < 2; ++ai)
; #pragma unroll
;             for (int m = 0; m < 4; ++m) { const int row = u.pm * 256 + ai * 128 + wr * 64 + m * 16 + fr;
;                 const float r2 = rsqrtf(ssq[row] * (1.0f / D) + EPS);
; #pragma unroll
;                 for (int bj = 0; bj < 2; ++bj) { const int col = u.pn * 256 + bj * 128 + wc * 32 + 8 * fq;
;                     f32x4 h0 = acc[ai][bj][m][0] * r2, h1 = acc[ai][bj][m][1] * r2;
; #pragma unroll
;                     for (int q = 0; q < 4; ++q) { const float a = fmaxf(h0[q], 0.f), b = fmaxf(h1[q], 0.f); h0[q] = a * a; h1[q] = b * b; }
;                     __builtin_nontemporal_store(pack8(h0, h1), (u32x4*)(HID + (size_t)row * DFF + col)); } }
;     }
	v_fmamk_f32 v102, v102, 0x3a000000, v134
	v_mul_f32_e32 v103, 0x4b800000, v102
	v_cmp_gt_f32_e32 vcc, s0, v102
	s_nop 1
	v_cndmask_b32_e32 v102, v102, v103, vcc
	v_rsq_f32_e32 v102, v102
	s_nop 0
	v_mul_f32_e32 v96, 0x45800000, v102
	v_cndmask_b32_e32 v96, v102, v96, vcc
	v_pk_mul_f32 v[94:95], v[94:95], v[96:97] op_sel_hi:[1,0]
	v_pk_mul_f32 v[92:93], v[92:93], v[96:97] op_sel_hi:[1,0]
	v_pk_mul_f32 v[90:91], v[90:91], v[96:97] op_sel_hi:[1,0]
	v_pk_mul_f32 v[88:89], v[88:89], v[96:97] op_sel_hi:[1,0]
	v_pk_mul_f32 v[86:87], v[86:87], v[96:97] op_sel_hi:[1,0]
	v_pk_mul_f32 v[82:83], v[82:83], v[96:97] op_sel_hi:[1,0]
	v_pk_mul_f32 v[80:81], v[80:81], v[96:97] op_sel_hi:[1,0]
	v_pk_mul_f32 v[84:85], v[84:85], v[96:97] op_sel_hi:[1,0]
	v_max_f32_e32 v92, 0, v92
	v_max_f32_e32 v88, 0, v88
	v_max_f32_e32 v93, 0, v93
	v_max_f32_e32 v89, 0, v89
	v_max_f32_e32 v94, 0, v94
	v_max_f32_e32 v90, 0, v90
	v_max_f32_e32 v95, 0, v95
	v_max_f32_e32 v91, 0, v91
	v_max_f32_e32 v80, 0, v80
	v_max_f32_e32 v81, 0, v81
	v_max_f32_e32 v86, 0, v86
	v_max_f32_e32 v82, 0, v82
	v_max_f32_e32 v83, 0, v83
	v_max_f32_e32 v84, 0, v84
	v_max_f32_e32 v85, 0, v85
	v_max_f32_e32 v87, 0, v87
	v_mul_f32_e32 v92, v92, v92
	v_mul_f32_e32 v88, v88, v88
	v_mul_f32_e32 v93, v93, v93
	v_mul_f32_e32 v89, v89, v89
	v_mul_f32_e32 v94, v94, v94
	v_mul_f32_e32 v90, v90, v90
	v_mul_f32_e32 v95, v95, v95
	v_mul_f32_e32 v91, v91, v91
	v_mul_f32_e32 v96, v80, v80
	v_mul_f32_e32 v97, v81, v81
	v_mul_f32_e32 v86, v86, v86
	v_mul_f32_e32 v98, v82, v82
	v_mul_f32_e32 v99, v83, v83
	v_cvt_pk_bf16_f32 v80, v92, v93
	v_cvt_pk_bf16_f32 v81, v94, v95
	v_cvt_pk_bf16_f32 v82, v88, v89
	v_cvt_pk_bf16_f32 v83, v90, v91
	v_mul_f32_e32 v84, v84, v84
	v_mul_f32_e32 v85, v85, v85
	v_mul_f32_e32 v87, v87, v87
	global_store_dwordx4 v[100:101], v[80:83], off offset:-4096 nt
	s_nop 1
	v_cvt_pk_bf16_f32 v80, v84, v85
	v_cvt_pk_bf16_f32 v81, v86, v87
	v_cvt_pk_bf16_f32 v82, v96, v97
	v_cvt_pk_bf16_f32 v83, v98, v99
	global_load_dword v86, v[132:133], off offset:192
	v_or_b32_e32 v84, 48, v128
	global_store_dwordx4 v[100:101], v[80:83], off nt
	v_mov_b32_e32 v85, v129
	v_lshlrev_b64 v[84:85], 14, v[84:85]
	v_lshl_add_u64 v[84:85], s[4:5], 0, v[84:85]
	v_lshl_add_u64 v[84:85], v[84:85], 0, v[130:131]
	s_waitcnt vmcnt(1)
	v_fmamk_f32 v86, v86, 0x3a000000, v134
	v_mul_f32_e32 v87, 0x4b800000, v86
	v_cmp_gt_f32_e32 vcc, s0, v86
	s_nop 1
	v_cndmask_b32_e32 v86, v86, v87, vcc
	v_rsq_f32_e32 v86, v86
	s_nop 0
	v_mul_f32_e32 v80, 0x45800000, v86
	v_cndmask_b32_e32 v80, v86, v80, vcc
	v_pk_mul_f32 v[78:79], v[78:79], v[80:81] op_sel_hi:[1,0]
	v_pk_mul_f32 v[76:77], v[76:77], v[80:81] op_sel_hi:[1,0]
	v_pk_mul_f32 v[74:75], v[74:75], v[80:81] op_sel_hi:[1,0]
	v_pk_mul_f32 v[72:73], v[72:73], v[80:81] op_sel_hi:[1,0]
	v_pk_mul_f32 v[70:71], v[70:71], v[80:81] op_sel_hi:[1,0]
	v_pk_mul_f32 v[66:67], v[66:67], v[80:81] op_sel_hi:[1,0]
	v_pk_mul_f32 v[64:65], v[64:65], v[80:81] op_sel_hi:[1,0]
	v_pk_mul_f32 v[68:69], v[68:69], v[80:81] op_sel_hi:[1,0]
	v_max_f32_e32 v76, 0, v76
	v_max_f32_e32 v72, 0, v72
	v_max_f32_e32 v77, 0, v77
	v_max_f32_e32 v73, 0, v73
	v_max_f32_e32 v78, 0, v78
	v_max_f32_e32 v74, 0, v74
	v_max_f32_e32 v79, 0, v79
	v_max_f32_e32 v75, 0, v75
	v_max_f32_e32 v64, 0, v64
	v_max_f32_e32 v65, 0, v65
	v_max_f32_e32 v70, 0, v70
	v_max_f32_e32 v66, 0, v66
	v_max_f32_e32 v67, 0, v67
	v_max_f32_e32 v68, 0, v68
	v_max_f32_e32 v69, 0, v69
	v_max_f32_e32 v71, 0, v71
	v_mul_f32_e32 v76, v76, v76
	v_mul_f32_e32 v72, v72, v72
	v_mul_f32_e32 v77, v77, v77
	v_mul_f32_e32 v73, v73, v73
	v_mul_f32_e32 v78, v78, v78
	v_mul_f32_e32 v74, v74, v74
	v_mul_f32_e32 v79, v79, v79
	v_mul_f32_e32 v75, v75, v75
	v_mul_f32_e32 v80, v64, v64
	v_mul_f32_e32 v81, v65, v65
	v_mul_f32_e32 v70, v70, v70
	v_mul_f32_e32 v82, v66, v66
	v_mul_f32_e32 v83, v67, v67
	v_cvt_pk_bf16_f32 v64, v76, v77
	v_cvt_pk_bf16_f32 v65, v78, v79
	v_cvt_pk_bf16_f32 v66, v72, v73
	v_cvt_pk_bf16_f32 v67, v74, v75
	v_mul_f32_e32 v68, v68, v68
	v_mul_f32_e32 v69, v69, v69
	v_mul_f32_e32 v71, v71, v71
	global_store_dwordx4 v[84:85], v[64:67], off offset:-4096 nt
	s_nop 1
	v_cvt_pk_bf16_f32 v64, v68, v69
	v_cvt_pk_bf16_f32 v65, v70, v71
	v_cvt_pk_bf16_f32 v66, v80, v81
	v_cvt_pk_bf16_f32 v67, v82, v83
	global_load_dword v70, v[132:133], off offset:512
	v_add_u32_e32 v68, 0x80, v128
	global_store_dwordx4 v[84:85], v[64:67], off nt
	v_mov_b32_e32 v69, v129
	v_lshlrev_b64 v[68:69], 14, v[68:69]
	v_lshl_add_u64 v[68:69], s[4:5], 0, v[68:69]
	v_lshl_add_u64 v[68:69], v[68:69], 0, v[130:131]
	s_waitcnt vmcnt(1)
; __device__ __forceinline__ u32x4 pack8(const f32x4 a, const f32x4 b) { u32x4 w; w.x = cvt_pk_bf16(a[0], a[1]); w.y = cvt_pk_bf16(a[2], a[3]); w.z = cvt_pk_bf16(b[0], b[1]); w.w = cvt_pk_bf16(b[2], b[3]); return w; }
;     __device__ __forceinline__ void operator()(AccRef acc, const Unit& u, int wr, int wc, int fr, int fq) const {
; #pragma unroll
;         for (int ai = 0; ai < 2; ++ai)
; #pragma unroll
;             for (int m = 0; m < 4; ++m) { const int row = u.pm * 256 + ai * 128 + wr * 64 + m * 16 + fr;
;                 const float r2 = rsqrtf(ssq[row] * (1.0f / D) + EPS);
; #pragma unroll
;                 for (int bj = 0; bj < 2; ++bj) { const int col = u.pn * 256 + bj * 128 + wc * 32 + 8 * fq;
;                     f32x4 h0 = acc[ai][bj][m][0] * r2, h1 = acc[ai][bj][m][1] * r2;
; #pragma unroll
;                     for (int q = 0; q < 4; ++q) { const float a = fmaxf(h0[q], 0.f), b = fmaxf(h1[q], 0.f); h0[q] = a * a; h1[q] = b * b; }
;                     __builtin_nontemporal_store(pack8(h0, h1), (u32x4*)(HID + (size_t)row * DFF + col)); } }
;     }
	v_fmamk_f32 v70, v70, 0x3a000000, v134
	v_mul_f32_e32 v71, 0x4b800000, v70
	v_cmp_gt_f32_e32 vcc, s0, v70
	s_nop 1
	v_cndmask_b32_e32 v70, v70, v71, vcc
	v_rsq_f32_e32 v70, v70
	s_nop 0
	v_mul_f32_e32 v64, 0x45800000, v70
	v_cndmask_b32_e32 v64, v70, v64, vcc
	v_pk_mul_f32 v[62:63], v[62:63], v[64:65] op_sel_hi:[1,0]
	v_pk_mul_f32 v[60:61], v[60:61], v[64:65] op_sel_hi:[1,0]
	v_pk_mul_f32 v[58:59], v[58:59], v[64:65] op_sel_hi:[1,0]
	v_pk_mul_f32 v[56:57], v[56:57], v[64:65] op_sel_hi:[1,0]
	v_pk_mul_f32 v[54:55], v[54:55], v[64:65] op_sel_hi:[1,0]
	v_pk_mul_f32 v[50:51], v[50:51], v[64:65] op_sel_hi:[1,0]
	v_pk_mul_f32 v[48:49], v[48:49], v[64:65] op_sel_hi:[1,0]
	v_pk_mul_f32 v[52:53], v[52:53], v[64:65] op_sel_hi:[1,0]
	v_max_f32_e32 v60, 0, v60
	v_max_f32_e32 v56, 0, v56
	v_max_f32_e32 v61, 0, v61
	v_max_f32_e32 v57, 0, v57
	v_max_f32_e32 v62, 0, v62
	v_max_f32_e32 v58, 0, v58
	v_max_f32_e32 v63, 0, v63
	v_max_f32_e32 v59, 0, v59
	v_max_f32_e32 v48, 0, v48
	v_max_f32_e32 v49, 0, v49
	v_max_f32_e32 v54, 0, v54
	v_max_f32_e32 v50, 0, v50
	v_max_f32_e32 v51, 0, v51
	v_max_f32_e32 v52, 0, v52
	v_max_f32_e32 v53, 0, v53
	v_max_f32_e32 v55, 0, v55
	v_mul_f32_e32 v60, v60, v60
	v_mul_f32_e32 v56, v56, v56
	v_mul_f32_e32 v61, v61, v61
	v_mul_f32_e32 v57, v57, v57
	v_mul_f32_e32 v62, v62, v62
	v_mul_f32_e32 v58, v58, v58
	v_mul_f32_e32 v63, v63, v63
	v_mul_f32_e32 v59, v59, v59
	v_mul_f32_e32 v64, v48, v48
	v_mul_f32_e32 v65, v49, v49
	v_mul_f32_e32 v54, v54, v54
	v_mul_f32_e32 v66, v50, v50
	v_mul_f32_e32 v67, v51, v51
	v_cvt_pk_bf16_f32 v48, v60, v61
	v_cvt_pk_bf16_f32 v49, v62, v63
	v_cvt_pk_bf16_f32 v50, v56, v57
	v_cvt_pk_bf16_f32 v51, v58, v59
	v_mul_f32_e32 v52, v52, v52
	v_mul_f32_e32 v53, v53, v53
	v_mul_f32_e32 v55, v55, v55
	global_store_dwordx4 v[68:69], v[48:51], off offset:-4096 nt
	s_nop 1
	v_cvt_pk_bf16_f32 v48, v52, v53
	v_cvt_pk_bf16_f32 v49, v54, v55
	v_cvt_pk_bf16_f32 v50, v64, v65
	v_cvt_pk_bf16_f32 v51, v66, v67
	global_load_dword v54, v[132:133], off offset:576
	v_add_u32_e32 v52, 0x90, v128
	global_store_dwordx4 v[68:69], v[48:51], off nt
	v_mov_b32_e32 v53, v129
	v_lshlrev_b64 v[52:53], 14, v[52:53]
	v_lshl_add_u64 v[52:53], s[4:5], 0, v[52:53]
	v_lshl_add_u64 v[52:53], v[52:53], 0, v[130:131]
	s_waitcnt vmcnt(1)
	v_fmamk_f32 v54, v54, 0x3a000000, v134
	v_mul_f32_e32 v55, 0x4b800000, v54
	v_cmp_gt_f32_e32 vcc, s0, v54
	s_nop 1
	v_cndmask_b32_e32 v54, v54, v55, vcc
	v_rsq_f32_e32 v54, v54
	s_nop 0
	v_mul_f32_e32 v48, 0x45800000, v54
	v_cndmask_b32_e32 v48, v54, v48, vcc
	v_pk_mul_f32 v[46:47], v[46:47], v[48:49] op_sel_hi:[1,0]
	v_pk_mul_f32 v[44:45], v[44:45], v[48:49] op_sel_hi:[1,0]
	v_pk_mul_f32 v[42:43], v[42:43], v[48:49] op_sel_hi:[1,0]
	v_pk_mul_f32 v[40:41], v[40:41], v[48:49] op_sel_hi:[1,0]
	v_pk_mul_f32 v[38:39], v[38:39], v[48:49] op_sel_hi:[1,0]
	v_pk_mul_f32 v[34:35], v[34:35], v[48:49] op_sel_hi:[1,0]
	v_pk_mul_f32 v[32:33], v[32:33], v[48:49] op_sel_hi:[1,0]
	v_pk_mul_f32 v[36:37], v[36:37], v[48:49] op_sel_hi:[1,0]
	v_max_f32_e32 v44, 0, v44
	v_max_f32_e32 v40, 0, v40
	v_max_f32_e32 v45, 0, v45
	v_max_f32_e32 v41, 0, v41
	v_max_f32_e32 v46, 0, v46
	v_max_f32_e32 v42, 0, v42
	v_max_f32_e32 v47, 0, v47
	v_max_f32_e32 v43, 0, v43
	v_max_f32_e32 v32, 0, v32
	v_max_f32_e32 v33, 0, v33
	v_max_f32_e32 v38, 0, v38
	v_max_f32_e32 v34, 0, v34
	v_max_f32_e32 v35, 0, v35
	v_max_f32_e32 v36, 0, v36
	v_max_f32_e32 v37, 0, v37
	v_max_f32_e32 v39, 0, v39
	v_mul_f32_e32 v44, v44, v44
	v_mul_f32_e32 v40, v40, v40
	v_mul_f32_e32 v45, v45, v45
	v_mul_f32_e32 v41, v41, v41
	v_mul_f32_e32 v46, v46, v46
	v_mul_f32_e32 v42, v42, v42
	v_mul_f32_e32 v47, v47, v47
	v_mul_f32_e32 v43, v43, v43
	v_mul_f32_e32 v48, v32, v32
	v_mul_f32_e32 v49, v33, v33
	v_mul_f32_e32 v38, v38, v38
	v_mul_f32_e32 v50, v34, v34
	v_mul_f32_e32 v51, v35, v35
	v_cvt_pk_bf16_f32 v32, v44, v45
	v_cvt_pk_bf16_f32 v33, v46, v47
	v_cvt_pk_bf16_f32 v34, v40, v41
	v_cvt_pk_bf16_f32 v35, v42, v43
	v_mul_f32_e32 v36, v36, v36
	v_mul_f32_e32 v37, v37, v37
	v_mul_f32_e32 v39, v39, v39
	global_store_dwordx4 v[52:53], v[32:35], off offset:-4096 nt
	s_nop 1
	v_cvt_pk_bf16_f32 v32, v36, v37
	v_cvt_pk_bf16_f32 v33, v38, v39
	v_cvt_pk_bf16_f32 v34, v48, v49
	v_cvt_pk_bf16_f32 v35, v50, v51
	global_load_dword v38, v[132:133], off offset:640
	v_add_u32_e32 v36, 0xa0, v128
	global_store_dwordx4 v[52:53], v[32:35], off nt
	v_mov_b32_e32 v37, v129
	v_lshlrev_b64 v[36:37], 14, v[36:37]
	v_lshl_add_u64 v[36:37], s[4:5], 0, v[36:37]
	v_lshl_add_u64 v[36:37], v[36:37], 0, v[130:131]
	v_add_u32_e32 v128, 0xb0, v128
	s_waitcnt vmcnt(1)
; __device__ __forceinline__ u32x4 pack8(const f32x4 a, const f32x4 b) { u32x4 w; w.x = cvt_pk_bf16(a[0], a[1]); w.y = cvt_pk_bf16(a[2], a[3]); w.z = cvt_pk_bf16(b[0], b[1]); w.w = cvt_pk_bf16(b[2], b[3]); return w; }
; #define PG8_WAIT_V(n) asm volatile("s_waitcnt vmcnt(" #n ")" ::: "memory")
; #define PG8_BAR __builtin_amdgcn_s_barrier()
; template <class Epi, class Sched>
; __device__ __forceinline__ void gemm_phase(LAS unsigned char* lds, const Gemm g, const Sched& S, const Epi& E) {
;     ...
;     PG8_WAIT_V(0);
;     PG8_BAR;
;     __device__ __forceinline__ void operator()(AccRef acc, const Unit& u, int wr, int wc, int fr, int fq) const {
; #pragma unroll
;         for (int ai = 0; ai < 2; ++ai)
; #pragma unroll
;             for (int m = 0; m < 4; ++m) { const int row = u.pm * 256 + ai * 128 + wr * 64 + m * 16 + fr;
;                 const float r2 = rsqrtf(ssq[row] * (1.0f / D) + EPS);
; #pragma unroll
;                 for (int bj = 0; bj < 2; ++bj) { const int col = u.pn * 256 + bj * 128 + wc * 32 + 8 * fq;
;                     f32x4 h0 = acc[ai][bj][m][0] * r2, h1 = acc[ai][bj][m][1] * r2;
; #pragma unroll
;                     for (int q = 0; q < 4; ++q) { const float a = fmaxf(h0[q], 0.f), b = fmaxf(h1[q], 0.f); h0[q] = a * a; h1[q] = b * b; }
;                     __builtin_nontemporal_store(pack8(h0, h1), (u32x4*)(HID + (size_t)row * DFF + col)); } }
;     }
	v_fmamk_f32 v38, v38, 0x3a000000, v134
	v_mul_f32_e32 v39, 0x4b800000, v38
	v_cmp_gt_f32_e32 vcc, s0, v38
	s_nop 1
	v_cndmask_b32_e32 v38, v38, v39, vcc
	v_rsq_f32_e32 v38, v38
	s_nop 0
	v_mul_f32_e32 v32, 0x45800000, v38
	v_cndmask_b32_e32 v32, v38, v32, vcc
	v_pk_mul_f32 v[30:31], v[30:31], v[32:33] op_sel_hi:[1,0]
	v_pk_mul_f32 v[28:29], v[28:29], v[32:33] op_sel_hi:[1,0]
	v_pk_mul_f32 v[26:27], v[26:27], v[32:33] op_sel_hi:[1,0]
	v_pk_mul_f32 v[24:25], v[24:25], v[32:33] op_sel_hi:[1,0]
	v_pk_mul_f32 v[22:23], v[22:23], v[32:33] op_sel_hi:[1,0]
	v_pk_mul_f32 v[18:19], v[18:19], v[32:33] op_sel_hi:[1,0]
	v_pk_mul_f32 v[16:17], v[16:17], v[32:33] op_sel_hi:[1,0]
	v_pk_mul_f32 v[20:21], v[20:21], v[32:33] op_sel_hi:[1,0]
	v_max_f32_e32 v28, 0, v28
	v_max_f32_e32 v24, 0, v24
	v_max_f32_e32 v29, 0, v29
	v_max_f32_e32 v25, 0, v25
	v_max_f32_e32 v30, 0, v30
	v_max_f32_e32 v26, 0, v26
	v_max_f32_e32 v31, 0, v31
	v_max_f32_e32 v27, 0, v27
	v_max_f32_e32 v16, 0, v16
	v_max_f32_e32 v17, 0, v17
	v_max_f32_e32 v22, 0, v22
	v_max_f32_e32 v18, 0, v18
	v_max_f32_e32 v19, 0, v19
	v_max_f32_e32 v20, 0, v20
	v_max_f32_e32 v21, 0, v21
	v_max_f32_e32 v23, 0, v23
	v_mul_f32_e32 v28, v28, v28
	v_mul_f32_e32 v24, v24, v24
	v_mul_f32_e32 v29, v29, v29
	v_mul_f32_e32 v25, v25, v25
	v_mul_f32_e32 v30, v30, v30
	v_mul_f32_e32 v26, v26, v26
	v_mul_f32_e32 v31, v31, v31
	v_mul_f32_e32 v27, v27, v27
	v_mul_f32_e32 v32, v16, v16
	v_mul_f32_e32 v33, v17, v17
	v_mul_f32_e32 v22, v22, v22
	v_mul_f32_e32 v34, v18, v18
	v_mul_f32_e32 v35, v19, v19
	v_cvt_pk_bf16_f32 v16, v28, v29
	v_cvt_pk_bf16_f32 v17, v30, v31
	v_cvt_pk_bf16_f32 v18, v24, v25
	v_cvt_pk_bf16_f32 v19, v26, v27
	v_mul_f32_e32 v20, v20, v20
	v_mul_f32_e32 v21, v21, v21
	v_mul_f32_e32 v23, v23, v23
	global_store_dwordx4 v[36:37], v[16:19], off offset:-4096 nt
	s_nop 1
	v_cvt_pk_bf16_f32 v16, v20, v21
	v_cvt_pk_bf16_f32 v17, v22, v23
	v_cvt_pk_bf16_f32 v18, v32, v33
	v_cvt_pk_bf16_f32 v19, v34, v35
	global_load_dword v22, v[132:133], off offset:704
	v_lshlrev_b64 v[20:21], 14, v[128:129]
	global_store_dwordx4 v[36:37], v[16:19], off nt
	v_lshl_add_u64 v[20:21], s[4:5], 0, v[20:21]
	v_lshl_add_u64 v[20:21], v[20:21], 0, v[130:131]
	s_waitcnt vmcnt(1)
	v_fmac_f32_e32 v134, 0x3a000000, v22
	v_mul_f32_e32 v22, 0x4b800000, v134
	v_cmp_gt_f32_e32 vcc, s0, v134
	s_nop 1
	v_cndmask_b32_e32 v22, v134, v22, vcc
	v_rsq_f32_e32 v22, v22
	s_nop 0
	v_mul_f32_e32 v16, 0x45800000, v22
	v_cndmask_b32_e32 v16, v22, v16, vcc
	v_pk_mul_f32 v[14:15], v[14:15], v[16:17] op_sel_hi:[1,0]
	v_pk_mul_f32 v[12:13], v[12:13], v[16:17] op_sel_hi:[1,0]
	v_pk_mul_f32 v[10:11], v[10:11], v[16:17] op_sel_hi:[1,0]
	v_pk_mul_f32 v[8:9], v[8:9], v[16:17] op_sel_hi:[1,0]
	v_pk_mul_f32 v[2:3], v[2:3], v[16:17] op_sel_hi:[1,0]
	v_pk_mul_f32 v[0:1], v[0:1], v[16:17] op_sel_hi:[1,0]
	v_pk_mul_f32 v[6:7], v[6:7], v[16:17] op_sel_hi:[1,0]
	v_pk_mul_f32 v[4:5], v[4:5], v[16:17] op_sel_hi:[1,0]
	v_max_f32_e32 v12, 0, v12
	v_max_f32_e32 v8, 0, v8
	v_max_f32_e32 v13, 0, v13
	v_max_f32_e32 v9, 0, v9
	v_max_f32_e32 v14, 0, v14
	v_max_f32_e32 v10, 0, v10
	v_max_f32_e32 v15, 0, v15
	v_max_f32_e32 v11, 0, v11
	v_max_f32_e32 v0, 0, v0
	v_max_f32_e32 v1, 0, v1
	v_max_f32_e32 v2, 0, v2
	v_max_f32_e32 v3, 0, v3
	v_max_f32_e32 v4, 0, v4
	v_max_f32_e32 v5, 0, v5
	v_max_f32_e32 v6, 0, v6
	v_max_f32_e32 v7, 0, v7
	v_mul_f32_e32 v12, v12, v12
	v_mul_f32_e32 v8, v8, v8
	v_mul_f32_e32 v13, v13, v13
	v_mul_f32_e32 v9, v9, v9
	v_mul_f32_e32 v14, v14, v14
	v_mul_f32_e32 v10, v10, v10
	v_mul_f32_e32 v15, v15, v15
	v_mul_f32_e32 v11, v11, v11
	v_mul_f32_e32 v16, v0, v0
	v_mul_f32_e32 v17, v1, v1
	v_mul_f32_e32 v18, v2, v2
	v_mul_f32_e32 v19, v3, v3
	v_cvt_pk_bf16_f32 v0, v12, v13
	v_cvt_pk_bf16_f32 v1, v14, v15
	v_cvt_pk_bf16_f32 v2, v8, v9
	v_cvt_pk_bf16_f32 v3, v10, v11
	v_mul_f32_e32 v4, v4, v4
	v_mul_f32_e32 v5, v5, v5
	v_mul_f32_e32 v6, v6, v6
	v_mul_f32_e32 v7, v7, v7
	global_store_dwordx4 v[20:21], v[0:3], off offset:-4096 nt
	s_nop 1
	v_cvt_pk_bf16_f32 v0, v4, v5
	v_cvt_pk_bf16_f32 v1, v6, v7
	v_cvt_pk_bf16_f32 v2, v16, v17
	v_cvt_pk_bf16_f32 v3, v18, v19
	global_store_dwordx4 v[20:21], v[0:3], off nt
	s_waitcnt vmcnt(0)
	s_barrier

; __device__ __forceinline__ u32x4 pack8(const f32x4 a, const f32x4 b) { u32x4 w; w.x = cvt_pk_bf16(a[0], a[1]); w.y = cvt_pk_bf16(a[2], a[3]); w.z = cvt_pk_bf16(b[0], b[1]); w.w = cvt_pk_bf16(b[2], b[3]); return w; }
;     __device__ __forceinline__ void operator()(AccRef acc, const Unit& u, int wr, int wc, int fr, int fq) const {
; #pragma unroll
;         for (int ai = 0; ai < 2; ++ai)
; #pragma unroll
;             for (int m = 0; m < 4; ++m) { const int row = u.pm * 256 + ai * 128 + wr * 64 + m * 16 + fr;
;                 const float r2 = rsqrtf(ssq[row] * (1.0f / D) + EPS);
; #pragma unroll
;                 for (int bj = 0; bj < 2; ++bj) { const int col = u.pn * 256 + bj * 128 + wc * 32 + 8 * fq;
;                     f32x4 h0 = acc[ai][bj][m][0] * r2, h1 = acc[ai][bj][m][1] * r2;
; #pragma unroll
;                     for (int q = 0; q < 4; ++q) { const float a = fmaxf(h0[q], 0.f), b = fmaxf(h1[q], 0.f); h0[q] = a * a; h1[q] = b * b; }
;                     __builtin_nontemporal_store(pack8(h0, h1), (u32x4*)(HID + (size_t)row * DFF + col)); } }
;     }
.LBB0_840:
	v_lshl_add_u32 v146, s24, 8, v137
	v_and_b32_e32 v146, -16, v146
	v_ashrrev_i32_e32 v147, 31, v146
	v_lshl_add_u64 v[150:151], v[146:147], 2, s[30:31]
	s_nop 0
	v_lshlrev_b64 v[160:161], 14, v[146:147]
	v_lshl_or_b32 v148, s2, 8, v154
	v_readlane_b32 s36, v242, 6
	v_lshrrev_b32_e32 v149, 5, v148
	v_lshlrev_b32_e32 v149, 10, v149
	v_readlane_b32 s37, v242, 7
	v_and_b32_e32 v148, 63, v136
	v_lshl_add_u32 v148, v148, 4, v149
	v_add_u32_e32 v148, 0x1000, v148
	v_mov_b32_e32 v149, 0
	s_nop 0
	v_fmamk_f32 v147, v230, 0x3a000000, v158
	v_mul_f32_e32 v159, 0x4b800000, v147
	v_cmp_gt_f32_e32 vcc, s50, v147
	v_lshl_add_u64 v[160:161], s[36:37], 0, v[160:161]
	v_lshl_add_u64 v[160:161], v[160:161], 0, v[148:149]
	v_cndmask_b32_e32 v147, v147, v159, vcc
	v_rsq_f32_e32 v147, v147
	s_nop 0
	v_mul_f32_e32 v159, 0x45800000, v147
	v_cndmask_b32_e32 v162, v147, v159, vcc
	v_pk_mul_f32 v[126:127], v[126:127], v[162:163] op_sel_hi:[1,0]
	v_pk_mul_f32 v[124:125], v[124:125], v[162:163] op_sel_hi:[1,0]
	v_pk_mul_f32 v[122:123], v[122:123], v[162:163] op_sel_hi:[1,0]
	v_pk_mul_f32 v[120:121], v[120:121], v[162:163] op_sel_hi:[1,0]
	v_pk_mul_f32 v[114:115], v[114:115], v[162:163] op_sel_hi:[1,0]
	v_pk_mul_f32 v[112:113], v[112:113], v[162:163] op_sel_hi:[1,0]
	v_pk_mul_f32 v[118:119], v[118:119], v[162:163] op_sel_hi:[1,0]
	v_pk_mul_f32 v[116:117], v[116:117], v[162:163] op_sel_hi:[1,0]
	v_max_f32_e32 v124, 0, v124
	v_max_f32_e32 v120, 0, v120
	v_max_f32_e32 v125, 0, v125
	v_max_f32_e32 v121, 0, v121
	v_max_f32_e32 v126, 0, v126
	v_max_f32_e32 v122, 0, v122
	v_max_f32_e32 v127, 0, v127
	v_max_f32_e32 v123, 0, v123
	v_max_f32_e32 v112, 0, v112
	v_max_f32_e32 v113, 0, v113
	v_max_f32_e32 v114, 0, v114
	v_max_f32_e32 v115, 0, v115
	v_max_f32_e32 v116, 0, v116
	v_max_f32_e32 v117, 0, v117
	v_max_f32_e32 v118, 0, v118
	v_max_f32_e32 v119, 0, v119
	v_mul_f32_e32 v124, v124, v124
	v_mul_f32_e32 v120, v120, v120
	v_mul_f32_e32 v125, v125, v125
	v_mul_f32_e32 v121, v121, v121
	v_mul_f32_e32 v126, v126, v126
	v_mul_f32_e32 v122, v122, v122
	v_mul_f32_e32 v127, v127, v127
	v_mul_f32_e32 v123, v123, v123
	v_mul_f32_e32 v147, v112, v112
	v_mul_f32_e32 v159, v113, v113
	v_mul_f32_e32 v162, v114, v114
	v_mul_f32_e32 v163, v115, v115
	v_cvt_pk_bf16_f32 v112, v124, v125
	v_cvt_pk_bf16_f32 v113, v126, v127
	v_cvt_pk_bf16_f32 v114, v120, v121
	v_cvt_pk_bf16_f32 v115, v122, v123
	v_mul_f32_e32 v116, v116, v116
	v_mul_f32_e32 v117, v117, v117
	v_mul_f32_e32 v118, v118, v118
	v_mul_f32_e32 v119, v119, v119
	global_store_dwordx4 v[160:161], v[112:115], off offset:-4096 nt
	s_nop 1
	v_cvt_pk_bf16_f32 v112, v116, v117
	v_cvt_pk_bf16_f32 v113, v118, v119
	v_cvt_pk_bf16_f32 v114, v147, v159
	v_cvt_pk_bf16_f32 v115, v162, v163
	global_store_dwordx4 v[160:161], v[112:115], off nt
	s_nop 0
	s_nop 0
	v_or_b32_e32 v112, 16, v146
	v_ashrrev_i32_e32 v113, 31, v112
	v_lshlrev_b64 v[112:113], 14, v[112:113]
	v_lshl_add_u64 v[112:113], s[36:37], 0, v[112:113]
	v_lshl_add_u64 v[112:113], v[112:113], 0, v[148:149]
	s_nop 0
	v_fmamk_f32 v114, v231, 0x3a000000, v158
	v_mul_f32_e32 v115, 0x4b800000, v114
	v_cmp_gt_f32_e32 vcc, s50, v114
	s_nop 1
	v_cndmask_b32_e32 v114, v114, v115, vcc
	v_rsq_f32_e32 v114, v114
	s_nop 0
	v_mul_f32_e32 v115, 0x45800000, v114
	v_cndmask_b32_e32 v114, v114, v115, vcc
	v_pk_mul_f32 v[110:111], v[110:111], v[114:115] op_sel_hi:[1,0]
	v_pk_mul_f32 v[108:109], v[108:109], v[114:115] op_sel_hi:[1,0]
	v_pk_mul_f32 v[106:107], v[106:107], v[114:115] op_sel_hi:[1,0]
	v_pk_mul_f32 v[104:105], v[104:105], v[114:115] op_sel_hi:[1,0]
	v_pk_mul_f32 v[98:99], v[98:99], v[114:115] op_sel_hi:[1,0]
	v_pk_mul_f32 v[96:97], v[96:97], v[114:115] op_sel_hi:[1,0]
	v_pk_mul_f32 v[102:103], v[102:103], v[114:115] op_sel_hi:[1,0]
	v_pk_mul_f32 v[100:101], v[100:101], v[114:115] op_sel_hi:[1,0]
	v_max_f32_e32 v108, 0, v108
	v_max_f32_e32 v104, 0, v104
	v_max_f32_e32 v109, 0, v109
	v_max_f32_e32 v105, 0, v105
	v_max_f32_e32 v110, 0, v110
	v_max_f32_e32 v106, 0, v106
	v_max_f32_e32 v111, 0, v111
	v_max_f32_e32 v107, 0, v107
	v_max_f32_e32 v96, 0, v96
	v_max_f32_e32 v97, 0, v97
	v_max_f32_e32 v98, 0, v98
	v_max_f32_e32 v99, 0, v99
	v_max_f32_e32 v100, 0, v100
	v_max_f32_e32 v101, 0, v101
	v_max_f32_e32 v102, 0, v102
	v_max_f32_e32 v103, 0, v103
	v_mul_f32_e32 v108, v108, v108
	v_mul_f32_e32 v104, v104, v104
	v_mul_f32_e32 v109, v109, v109
	v_mul_f32_e32 v105, v105, v105
	v_mul_f32_e32 v110, v110, v110
	v_mul_f32_e32 v106, v106, v106
	v_mul_f32_e32 v111, v111, v111
	v_mul_f32_e32 v107, v107, v107
	v_mul_f32_e32 v114, v96, v96
	v_mul_f32_e32 v115, v97, v97
	v_mul_f32_e32 v116, v98, v98
	v_mul_f32_e32 v117, v99, v99
	v_cvt_pk_bf16_f32 v96, v108, v109
	v_cvt_pk_bf16_f32 v97, v110, v111
	v_cvt_pk_bf16_f32 v98, v104, v105
	v_cvt_pk_bf16_f32 v99, v106, v107
	v_mul_f32_e32 v100, v100, v100
	v_mul_f32_e32 v101, v101, v101
	v_mul_f32_e32 v102, v102, v102
	v_mul_f32_e32 v103, v103, v103
	global_store_dwordx4 v[112:113], v[96:99], off offset:-4096 nt
	s_nop 1
	v_cvt_pk_bf16_f32 v96, v100, v101
	v_cvt_pk_bf16_f32 v97, v102, v103
	v_cvt_pk_bf16_f32 v98, v114, v115
	v_cvt_pk_bf16_f32 v99, v116, v117
	global_store_dwordx4 v[112:113], v[96:99], off nt
	s_nop 0
	s_nop 0
	v_or_b32_e32 v96, 32, v146
	v_ashrrev_i32_e32 v97, 31, v96
	v_lshlrev_b64 v[96:97], 14, v[96:97]
	v_lshl_add_u64 v[96:97], s[36:37], 0, v[96:97]
	v_lshl_add_u64 v[96:97], v[96:97], 0, v[148:149]
	s_nop 0
	v_fmamk_f32 v98, v232, 0x3a000000, v158
	v_mul_f32_e32 v99, 0x4b800000, v98
	v_cmp_gt_f32_e32 vcc, s50, v98
	s_nop 1
	v_cndmask_b32_e32 v98, v98, v99, vcc
	v_rsq_f32_e32 v98, v98
	s_nop 0
	v_mul_f32_e32 v99, 0x45800000, v98
; __device__ __forceinline__ u32x4 pack8(const f32x4 a, const f32x4 b) { u32x4 w; w.x = cvt_pk_bf16(a[0], a[1]); w.y = cvt_pk_bf16(a[2], a[3]); w.z = cvt_pk_bf16(b[0], b[1]); w.w = cvt_pk_bf16(b[2], b[3]); return w; }
;     __device__ __forceinline__ void operator()(AccRef acc, const Unit& u, int wr, int wc, int fr, int fq) const {
;     ...
;             for (int m = 0; m < 4; ++m) { const int row = u.pm * 256 + ai * 128 + wr * 64 + m * 16 + fr;
;                 const float r2 = rsqrtf(ssq[row] * (1.0f / D) + EPS);
; #pragma unroll
;                 for (int bj = 0; bj < 2; ++bj) { const int col = u.pn * 256 + bj * 128 + wc * 32 + 8 * fq;
;                     f32x4 h0 = acc[ai][bj][m][0] * r2, h1 = acc[ai][bj][m][1] * r2;
; #pragma unroll
;                     for (int q = 0; q < 4; ++q) { const float a = fmaxf(h0[q], 0.f), b = fmaxf(h1[q], 0.f); h0[q] = a * a; h1[q] = b * b; }
;                     __builtin_nontemporal_store(pack8(h0, h1), (u32x4*)(HID + (size_t)row * DFF + col)); } }
	v_cndmask_b32_e32 v98, v98, v99, vcc
	v_pk_mul_f32 v[94:95], v[94:95], v[98:99] op_sel_hi:[1,0]
	v_pk_mul_f32 v[92:93], v[92:93], v[98:99] op_sel_hi:[1,0]
	v_pk_mul_f32 v[90:91], v[90:91], v[98:99] op_sel_hi:[1,0]
	v_pk_mul_f32 v[88:89], v[88:89], v[98:99] op_sel_hi:[1,0]
	v_pk_mul_f32 v[82:83], v[82:83], v[98:99] op_sel_hi:[1,0]
	v_pk_mul_f32 v[80:81], v[80:81], v[98:99] op_sel_hi:[1,0]
	v_pk_mul_f32 v[86:87], v[86:87], v[98:99] op_sel_hi:[1,0]
	v_pk_mul_f32 v[84:85], v[84:85], v[98:99] op_sel_hi:[1,0]
	v_max_f32_e32 v92, 0, v92
	v_max_f32_e32 v88, 0, v88
	v_max_f32_e32 v93, 0, v93
	v_max_f32_e32 v89, 0, v89
	v_max_f32_e32 v94, 0, v94
	v_max_f32_e32 v90, 0, v90
	v_max_f32_e32 v95, 0, v95
	v_max_f32_e32 v91, 0, v91
	v_max_f32_e32 v80, 0, v80
	v_max_f32_e32 v81, 0, v81
	v_max_f32_e32 v82, 0, v82
	v_max_f32_e32 v83, 0, v83
	v_max_f32_e32 v84, 0, v84
	v_max_f32_e32 v85, 0, v85
	v_max_f32_e32 v86, 0, v86
	v_max_f32_e32 v87, 0, v87
	v_mul_f32_e32 v92, v92, v92
	v_mul_f32_e32 v88, v88, v88
	v_mul_f32_e32 v93, v93, v93
	v_mul_f32_e32 v89, v89, v89
	v_mul_f32_e32 v94, v94, v94
	v_mul_f32_e32 v90, v90, v90
	v_mul_f32_e32 v95, v95, v95
	v_mul_f32_e32 v91, v91, v91
	v_mul_f32_e32 v98, v80, v80
	v_mul_f32_e32 v99, v81, v81
	v_mul_f32_e32 v100, v82, v82
	v_mul_f32_e32 v101, v83, v83
	v_cvt_pk_bf16_f32 v80, v92, v93
	v_cvt_pk_bf16_f32 v81, v94, v95
	v_cvt_pk_bf16_f32 v82, v88, v89
	v_cvt_pk_bf16_f32 v83, v90, v91
	v_mul_f32_e32 v84, v84, v84
	v_mul_f32_e32 v85, v85, v85
	v_mul_f32_e32 v86, v86, v86
	v_mul_f32_e32 v87, v87, v87
	global_store_dwordx4 v[96:97], v[80:83], off offset:-4096 nt
	s_nop 1
	v_cvt_pk_bf16_f32 v80, v84, v85
	v_cvt_pk_bf16_f32 v81, v86, v87
	v_cvt_pk_bf16_f32 v82, v98, v99
	v_cvt_pk_bf16_f32 v83, v100, v101
	global_store_dwordx4 v[96:97], v[80:83], off nt
	s_nop 0
	s_nop 0
	v_or_b32_e32 v80, 48, v146
	v_ashrrev_i32_e32 v81, 31, v80
	v_lshlrev_b64 v[80:81], 14, v[80:81]
	v_lshl_add_u64 v[80:81], s[36:37], 0, v[80:81]
	v_lshl_add_u64 v[80:81], v[80:81], 0, v[148:149]
	s_nop 0
	v_fmamk_f32 v82, v233, 0x3a000000, v158
	v_mul_f32_e32 v83, 0x4b800000, v82
	v_cmp_gt_f32_e32 vcc, s50, v82
	s_nop 1
	v_cndmask_b32_e32 v82, v82, v83, vcc
	v_rsq_f32_e32 v82, v82
	s_nop 0
	v_mul_f32_e32 v83, 0x45800000, v82
	v_cndmask_b32_e32 v82, v82, v83, vcc
	v_pk_mul_f32 v[78:79], v[78:79], v[82:83] op_sel_hi:[1,0]
	v_pk_mul_f32 v[76:77], v[76:77], v[82:83] op_sel_hi:[1,0]
	v_pk_mul_f32 v[74:75], v[74:75], v[82:83] op_sel_hi:[1,0]
	v_pk_mul_f32 v[72:73], v[72:73], v[82:83] op_sel_hi:[1,0]
	v_pk_mul_f32 v[66:67], v[66:67], v[82:83] op_sel_hi:[1,0]
	v_pk_mul_f32 v[64:65], v[64:65], v[82:83] op_sel_hi:[1,0]
	v_pk_mul_f32 v[70:71], v[70:71], v[82:83] op_sel_hi:[1,0]
	v_pk_mul_f32 v[68:69], v[68:69], v[82:83] op_sel_hi:[1,0]
	v_max_f32_e32 v76, 0, v76
	v_max_f32_e32 v72, 0, v72
	v_max_f32_e32 v77, 0, v77
	v_max_f32_e32 v73, 0, v73
	v_max_f32_e32 v78, 0, v78
	v_max_f32_e32 v74, 0, v74
	v_max_f32_e32 v79, 0, v79
	v_max_f32_e32 v75, 0, v75
	v_max_f32_e32 v64, 0, v64
	v_max_f32_e32 v65, 0, v65
	v_max_f32_e32 v66, 0, v66
	v_max_f32_e32 v67, 0, v67
	v_max_f32_e32 v68, 0, v68
	v_max_f32_e32 v69, 0, v69
	v_max_f32_e32 v70, 0, v70
	v_max_f32_e32 v71, 0, v71
	v_mul_f32_e32 v76, v76, v76
	v_mul_f32_e32 v72, v72, v72
	v_mul_f32_e32 v77, v77, v77
	v_mul_f32_e32 v73, v73, v73
	v_mul_f32_e32 v78, v78, v78
	v_mul_f32_e32 v74, v74, v74
	v_mul_f32_e32 v79, v79, v79
	v_mul_f32_e32 v75, v75, v75
	v_mul_f32_e32 v82, v64, v64
	v_mul_f32_e32 v83, v65, v65
	v_mul_f32_e32 v84, v66, v66
	v_mul_f32_e32 v85, v67, v67
	v_cvt_pk_bf16_f32 v64, v76, v77
	v_cvt_pk_bf16_f32 v65, v78, v79
	v_cvt_pk_bf16_f32 v66, v72, v73
	v_cvt_pk_bf16_f32 v67, v74, v75
	v_mul_f32_e32 v68, v68, v68
	v_mul_f32_e32 v69, v69, v69
	v_mul_f32_e32 v70, v70, v70
	v_mul_f32_e32 v71, v71, v71
	global_store_dwordx4 v[80:81], v[64:67], off offset:-4096 nt
	s_nop 1
	v_cvt_pk_bf16_f32 v64, v68, v69
	v_cvt_pk_bf16_f32 v65, v70, v71
	v_cvt_pk_bf16_f32 v66, v82, v83
	v_cvt_pk_bf16_f32 v67, v84, v85
	global_store_dwordx4 v[80:81], v[64:67], off nt
	s_nop 0
	s_nop 0
	v_add_u32_e32 v64, 0x80, v146
	v_ashrrev_i32_e32 v65, 31, v64
	v_lshlrev_b64 v[64:65], 14, v[64:65]
	v_lshl_add_u64 v[64:65], s[36:37], 0, v[64:65]
	v_lshl_add_u64 v[64:65], v[64:65], 0, v[148:149]
	s_nop 0
	v_fmamk_f32 v66, v234, 0x3a000000, v158
	v_mul_f32_e32 v67, 0x4b800000, v66
	v_cmp_gt_f32_e32 vcc, s50, v66
	s_nop 1
	v_cndmask_b32_e32 v66, v66, v67, vcc
	v_rsq_f32_e32 v66, v66
	s_nop 0
	v_mul_f32_e32 v67, 0x45800000, v66
	v_cndmask_b32_e32 v66, v66, v67, vcc
	v_pk_mul_f32 v[62:63], v[62:63], v[66:67] op_sel_hi:[1,0]
	v_pk_mul_f32 v[60:61], v[60:61], v[66:67] op_sel_hi:[1,0]
	v_pk_mul_f32 v[58:59], v[58:59], v[66:67] op_sel_hi:[1,0]
	v_pk_mul_f32 v[56:57], v[56:57], v[66:67] op_sel_hi:[1,0]
	v_pk_mul_f32 v[50:51], v[50:51], v[66:67] op_sel_hi:[1,0]
	v_pk_mul_f32 v[48:49], v[48:49], v[66:67] op_sel_hi:[1,0]
	v_pk_mul_f32 v[54:55], v[54:55], v[66:67] op_sel_hi:[1,0]
	v_pk_mul_f32 v[52:53], v[52:53], v[66:67] op_sel_hi:[1,0]
	v_max_f32_e32 v60, 0, v60
	v_max_f32_e32 v56, 0, v56
	v_max_f32_e32 v61, 0, v61
	v_max_f32_e32 v57, 0, v57
	v_max_f32_e32 v62, 0, v62
	v_max_f32_e32 v58, 0, v58
	v_max_f32_e32 v63, 0, v63
	v_max_f32_e32 v59, 0, v59
	v_max_f32_e32 v48, 0, v48
	v_max_f32_e32 v49, 0, v49
	v_max_f32_e32 v50, 0, v50
	v_max_f32_e32 v51, 0, v51
	v_max_f32_e32 v52, 0, v52
	v_max_f32_e32 v53, 0, v53
	v_max_f32_e32 v54, 0, v54
	v_max_f32_e32 v55, 0, v55
	v_mul_f32_e32 v60, v60, v60
	v_mul_f32_e32 v56, v56, v56
	v_mul_f32_e32 v61, v61, v61
	v_mul_f32_e32 v57, v57, v57
	v_mul_f32_e32 v62, v62, v62
	v_mul_f32_e32 v58, v58, v58
	v_mul_f32_e32 v63, v63, v63
; __device__ __forceinline__ u32x4 pack8(const f32x4 a, const f32x4 b) { u32x4 w; w.x = cvt_pk_bf16(a[0], a[1]); w.y = cvt_pk_bf16(a[2], a[3]); w.z = cvt_pk_bf16(b[0], b[1]); w.w = cvt_pk_bf16(b[2], b[3]); return w; }
;     __device__ __forceinline__ void operator()(AccRef acc, const Unit& u, int wr, int wc, int fr, int fq) const {
;     ...
;             for (int m = 0; m < 4; ++m) { const int row = u.pm * 256 + ai * 128 + wr * 64 + m * 16 + fr;
;                 const float r2 = rsqrtf(ssq[row] * (1.0f / D) + EPS);
; #pragma unroll
;                 for (int bj = 0; bj < 2; ++bj) { const int col = u.pn * 256 + bj * 128 + wc * 32 + 8 * fq;
;                     f32x4 h0 = acc[ai][bj][m][0] * r2, h1 = acc[ai][bj][m][1] * r2;
; #pragma unroll
;                     for (int q = 0; q < 4; ++q) { const float a = fmaxf(h0[q], 0.f), b = fmaxf(h1[q], 0.f); h0[q] = a * a; h1[q] = b * b; }
;                     __builtin_nontemporal_store(pack8(h0, h1), (u32x4*)(HID + (size_t)row * DFF + col)); } }
	v_mul_f32_e32 v59, v59, v59
	v_mul_f32_e32 v66, v48, v48
	v_mul_f32_e32 v67, v49, v49
	v_mul_f32_e32 v68, v50, v50
	v_mul_f32_e32 v69, v51, v51
	v_cvt_pk_bf16_f32 v48, v60, v61
	v_cvt_pk_bf16_f32 v49, v62, v63
	v_cvt_pk_bf16_f32 v50, v56, v57
	v_cvt_pk_bf16_f32 v51, v58, v59
	v_mul_f32_e32 v52, v52, v52
	v_mul_f32_e32 v53, v53, v53
	v_mul_f32_e32 v54, v54, v54
	v_mul_f32_e32 v55, v55, v55
	global_store_dwordx4 v[64:65], v[48:51], off offset:-4096 nt
	s_nop 1
	v_cvt_pk_bf16_f32 v48, v52, v53
	v_cvt_pk_bf16_f32 v49, v54, v55
	v_cvt_pk_bf16_f32 v50, v66, v67
	v_cvt_pk_bf16_f32 v51, v68, v69
	global_store_dwordx4 v[64:65], v[48:51], off nt
	s_nop 0
	s_nop 0
	v_add_u32_e32 v48, 0x90, v146
	v_ashrrev_i32_e32 v49, 31, v48
	v_lshlrev_b64 v[48:49], 14, v[48:49]
	v_lshl_add_u64 v[48:49], s[36:37], 0, v[48:49]
	v_lshl_add_u64 v[48:49], v[48:49], 0, v[148:149]
	s_nop 0
	v_fmamk_f32 v50, v235, 0x3a000000, v158
	v_mul_f32_e32 v51, 0x4b800000, v50
	v_cmp_gt_f32_e32 vcc, s50, v50
	s_nop 1
	v_cndmask_b32_e32 v50, v50, v51, vcc
	v_rsq_f32_e32 v50, v50
	s_nop 0
	v_mul_f32_e32 v51, 0x45800000, v50
	v_cndmask_b32_e32 v50, v50, v51, vcc
	v_pk_mul_f32 v[46:47], v[46:47], v[50:51] op_sel_hi:[1,0]
	v_pk_mul_f32 v[44:45], v[44:45], v[50:51] op_sel_hi:[1,0]
	v_pk_mul_f32 v[42:43], v[42:43], v[50:51] op_sel_hi:[1,0]
	v_pk_mul_f32 v[40:41], v[40:41], v[50:51] op_sel_hi:[1,0]
	v_pk_mul_f32 v[34:35], v[34:35], v[50:51] op_sel_hi:[1,0]
	v_pk_mul_f32 v[32:33], v[32:33], v[50:51] op_sel_hi:[1,0]
	v_pk_mul_f32 v[38:39], v[38:39], v[50:51] op_sel_hi:[1,0]
	v_pk_mul_f32 v[36:37], v[36:37], v[50:51] op_sel_hi:[1,0]
	v_max_f32_e32 v44, 0, v44
	v_max_f32_e32 v40, 0, v40
	v_max_f32_e32 v45, 0, v45
	v_max_f32_e32 v41, 0, v41
	v_max_f32_e32 v46, 0, v46
	v_max_f32_e32 v42, 0, v42
	v_max_f32_e32 v47, 0, v47
	v_max_f32_e32 v43, 0, v43
	v_max_f32_e32 v32, 0, v32
	v_max_f32_e32 v33, 0, v33
	v_max_f32_e32 v34, 0, v34
	v_max_f32_e32 v35, 0, v35
	v_max_f32_e32 v36, 0, v36
	v_max_f32_e32 v37, 0, v37
	v_max_f32_e32 v38, 0, v38
	v_max_f32_e32 v39, 0, v39
	v_mul_f32_e32 v44, v44, v44
	v_mul_f32_e32 v40, v40, v40
	v_mul_f32_e32 v45, v45, v45
	v_mul_f32_e32 v41, v41, v41
	v_mul_f32_e32 v46, v46, v46
	v_mul_f32_e32 v42, v42, v42
	v_mul_f32_e32 v47, v47, v47
	v_mul_f32_e32 v43, v43, v43
	v_mul_f32_e32 v50, v32, v32
	v_mul_f32_e32 v51, v33, v33
	v_mul_f32_e32 v52, v34, v34
	v_mul_f32_e32 v53, v35, v35
	v_cvt_pk_bf16_f32 v32, v44, v45
	v_cvt_pk_bf16_f32 v33, v46, v47
	v_cvt_pk_bf16_f32 v34, v40, v41
	v_cvt_pk_bf16_f32 v35, v42, v43
	v_mul_f32_e32 v36, v36, v36
	v_mul_f32_e32 v37, v37, v37
	v_mul_f32_e32 v38, v38, v38
	v_mul_f32_e32 v39, v39, v39
	global_store_dwordx4 v[48:49], v[32:35], off offset:-4096 nt
	s_nop 1
	v_cvt_pk_bf16_f32 v32, v36, v37
	v_cvt_pk_bf16_f32 v33, v38, v39
	v_cvt_pk_bf16_f32 v34, v50, v51
	v_cvt_pk_bf16_f32 v35, v52, v53
	global_store_dwordx4 v[48:49], v[32:35], off nt
	s_nop 0
	s_nop 0
	v_add_u32_e32 v32, 0xa0, v146
	v_ashrrev_i32_e32 v33, 31, v32
	v_lshlrev_b64 v[32:33], 14, v[32:33]
	v_lshl_add_u64 v[32:33], s[36:37], 0, v[32:33]
	v_lshl_add_u64 v[32:33], v[32:33], 0, v[148:149]
	s_nop 0
	v_fmamk_f32 v34, v236, 0x3a000000, v158
	v_mul_f32_e32 v35, 0x4b800000, v34
	v_cmp_gt_f32_e32 vcc, s50, v34
	s_nop 1
	v_cndmask_b32_e32 v34, v34, v35, vcc
	v_rsq_f32_e32 v34, v34
	s_nop 0
	v_mul_f32_e32 v35, 0x45800000, v34
	v_cndmask_b32_e32 v34, v34, v35, vcc
	v_pk_mul_f32 v[30:31], v[30:31], v[34:35] op_sel_hi:[1,0]
	v_pk_mul_f32 v[28:29], v[28:29], v[34:35] op_sel_hi:[1,0]
	v_pk_mul_f32 v[26:27], v[26:27], v[34:35] op_sel_hi:[1,0]
	v_pk_mul_f32 v[24:25], v[24:25], v[34:35] op_sel_hi:[1,0]
	v_pk_mul_f32 v[18:19], v[18:19], v[34:35] op_sel_hi:[1,0]
	v_pk_mul_f32 v[16:17], v[16:17], v[34:35] op_sel_hi:[1,0]
; __device__ __forceinline__ u32x4 pack8(const f32x4 a, const f32x4 b) { u32x4 w; w.x = cvt_pk_bf16(a[0], a[1]); w.y = cvt_pk_bf16(a[2], a[3]); w.z = cvt_pk_bf16(b[0], b[1]); w.w = cvt_pk_bf16(b[2], b[3]); return w; }
; #define PG8_BAR __builtin_amdgcn_s_barrier()
; template <class Epi, class Sched>
; __device__ __forceinline__ void gemm_phase(LAS unsigned char* lds, const Gemm g, const Sched& S, const Epi& E) {
;     ...
;         if (!has_next) break;
; #pragma unroll
;         for (int a = 0; a < 2; ++a)
; #pragma unroll
;             for (int b = 0; b < 2; ++b)
; #pragma unroll
;                 for (int m = 0; m < 4; ++m)
; #pragma unroll
;                     for (int n = 0; n < 2; ++n) acc[a][b][m][n] = (f32x4){0.f, 0.f, 0.f, 0.f};
;         cur = nxt; cA = nA; cB = nB; ++ui;
;         if (wr == 1) PG8_BAR;
;     __device__ __forceinline__ void operator()(AccRef acc, const Unit& u, int wr, int wc, int fr, int fq) const {
;     ...
;             for (int m = 0; m < 4; ++m) { const int row = u.pm * 256 + ai * 128 + wr * 64 + m * 16 + fr;
;                 const float r2 = rsqrtf(ssq[row] * (1.0f / D) + EPS);
; #pragma unroll
;                 for (int bj = 0; bj < 2; ++bj) { const int col = u.pn * 256 + bj * 128 + wc * 32 + 8 * fq;
;                     f32x4 h0 = acc[ai][bj][m][0] * r2, h1 = acc[ai][bj][m][1] * r2;
; #pragma unroll
;                     for (int q = 0; q < 4; ++q) { const float a = fmaxf(h0[q], 0.f), b = fmaxf(h1[q], 0.f); h0[q] = a * a; h1[q] = b * b; }
;                     __builtin_nontemporal_store(pack8(h0, h1), (u32x4*)(HID + (size_t)row * DFF + col)); } }
	v_pk_mul_f32 v[22:23], v[22:23], v[34:35] op_sel_hi:[1,0]
	v_pk_mul_f32 v[20:21], v[20:21], v[34:35] op_sel_hi:[1,0]
	v_max_f32_e32 v28, 0, v28
	v_max_f32_e32 v24, 0, v24
	v_max_f32_e32 v29, 0, v29
	v_max_f32_e32 v25, 0, v25
	v_max_f32_e32 v30, 0, v30
	v_max_f32_e32 v26, 0, v26
	v_max_f32_e32 v31, 0, v31
	v_max_f32_e32 v27, 0, v27
	v_max_f32_e32 v16, 0, v16
	v_max_f32_e32 v17, 0, v17
	v_max_f32_e32 v18, 0, v18
	v_max_f32_e32 v19, 0, v19
	v_max_f32_e32 v20, 0, v20
	v_max_f32_e32 v21, 0, v21
	v_max_f32_e32 v22, 0, v22
	v_max_f32_e32 v23, 0, v23
	v_mul_f32_e32 v28, v28, v28
	v_mul_f32_e32 v24, v24, v24
	v_mul_f32_e32 v29, v29, v29
	v_mul_f32_e32 v25, v25, v25
	v_mul_f32_e32 v30, v30, v30
	v_mul_f32_e32 v26, v26, v26
	v_mul_f32_e32 v31, v31, v31
	v_mul_f32_e32 v27, v27, v27
	v_mul_f32_e32 v34, v16, v16
	v_mul_f32_e32 v35, v17, v17
	v_mul_f32_e32 v36, v18, v18
	v_mul_f32_e32 v37, v19, v19
	v_cvt_pk_bf16_f32 v16, v28, v29
	v_cvt_pk_bf16_f32 v17, v30, v31
	v_cvt_pk_bf16_f32 v18, v24, v25
	v_cvt_pk_bf16_f32 v19, v26, v27
	v_mul_f32_e32 v20, v20, v20
	v_mul_f32_e32 v21, v21, v21
	v_mul_f32_e32 v22, v22, v22
	v_mul_f32_e32 v23, v23, v23
	global_store_dwordx4 v[32:33], v[16:19], off offset:-4096 nt
	s_andn2_b64 vcc, exec, s[0:1]
	s_nop 0
	v_cvt_pk_bf16_f32 v16, v20, v21
	v_cvt_pk_bf16_f32 v17, v22, v23
	v_cvt_pk_bf16_f32 v18, v34, v35
	v_cvt_pk_bf16_f32 v19, v36, v37
	global_store_dwordx4 v[32:33], v[16:19], off nt
	s_nop 0
	s_nop 0
	v_add_u32_e32 v16, 0xb0, v146
	v_ashrrev_i32_e32 v17, 31, v16
	v_lshlrev_b64 v[16:17], 14, v[16:17]
	v_lshl_add_u64 v[16:17], s[36:37], 0, v[16:17]
	v_lshl_add_u64 v[16:17], v[16:17], 0, v[148:149]
	s_nop 0
	v_fmamk_f32 v18, v237, 0x3a000000, v158
	v_mul_f32_e32 v19, 0x4b800000, v18
	v_cmp_gt_f32_e64 s[0:1], s50, v18
	s_nop 1
	v_cndmask_b32_e64 v18, v18, v19, s[0:1]
	v_rsq_f32_e32 v18, v18
	s_nop 0
	v_mul_f32_e32 v19, 0x45800000, v18
	v_cndmask_b32_e64 v18, v18, v19, s[0:1]
	v_pk_mul_f32 v[14:15], v[14:15], v[18:19] op_sel_hi:[1,0]
	v_pk_mul_f32 v[12:13], v[12:13], v[18:19] op_sel_hi:[1,0]
	v_pk_mul_f32 v[10:11], v[10:11], v[18:19] op_sel_hi:[1,0]
	v_pk_mul_f32 v[8:9], v[8:9], v[18:19] op_sel_hi:[1,0]
	v_pk_mul_f32 v[2:3], v[2:3], v[18:19] op_sel_hi:[1,0]
	v_pk_mul_f32 v[0:1], v[0:1], v[18:19] op_sel_hi:[1,0]
	v_pk_mul_f32 v[6:7], v[6:7], v[18:19] op_sel_hi:[1,0]
	v_pk_mul_f32 v[4:5], v[4:5], v[18:19] op_sel_hi:[1,0]
	v_max_f32_e32 v12, 0, v12
	v_max_f32_e32 v8, 0, v8
	v_max_f32_e32 v13, 0, v13
	v_max_f32_e32 v9, 0, v9
	v_max_f32_e32 v14, 0, v14
	v_max_f32_e32 v10, 0, v10
	v_max_f32_e32 v15, 0, v15
	v_max_f32_e32 v11, 0, v11
	v_max_f32_e32 v0, 0, v0
	v_max_f32_e32 v1, 0, v1
	v_max_f32_e32 v2, 0, v2
	v_max_f32_e32 v3, 0, v3
	v_max_f32_e32 v4, 0, v4
	v_max_f32_e32 v5, 0, v5
	v_max_f32_e32 v6, 0, v6
	v_max_f32_e32 v7, 0, v7
	v_mul_f32_e32 v12, v12, v12
	v_mul_f32_e32 v8, v8, v8
	v_mul_f32_e32 v13, v13, v13
	v_mul_f32_e32 v9, v9, v9
	v_mul_f32_e32 v14, v14, v14
	v_mul_f32_e32 v10, v10, v10
	v_mul_f32_e32 v15, v15, v15
	v_mul_f32_e32 v11, v11, v11
	v_mul_f32_e32 v18, v0, v0
	v_mul_f32_e32 v19, v1, v1
	v_mul_f32_e32 v20, v2, v2
	v_mul_f32_e32 v21, v3, v3
	v_cvt_pk_bf16_f32 v0, v12, v13
	v_cvt_pk_bf16_f32 v1, v14, v15
	v_cvt_pk_bf16_f32 v2, v8, v9
	v_cvt_pk_bf16_f32 v3, v10, v11
	s_mov_b64 s[0:1], -1
	v_mul_f32_e32 v4, v4, v4
	v_mul_f32_e32 v5, v5, v5
	v_mul_f32_e32 v6, v6, v6
	v_mul_f32_e32 v7, v7, v7
	global_store_dwordx4 v[16:17], v[0:3], off offset:-4096 nt
	s_nop 1
	v_cvt_pk_bf16_f32 v0, v4, v5
	v_cvt_pk_bf16_f32 v1, v6, v7
	v_cvt_pk_bf16_f32 v2, v18, v19
	v_cvt_pk_bf16_f32 v3, v20, v21
	global_store_dwordx4 v[16:17], v[0:3], off nt
	s_cbranch_vccnz .LBB0_829
	s_andn2_b64 vcc, exec, s[8:9]
	s_cbranch_vccnz .LBB0_828
	s_barrier
	s_branch .LBB0_828

;     __device__ bool next(int i, Unit& u) const { return at((long)i * G + c, u); }
;     __device__ bool next(int i, Unit& u) const { if (i > 0) return false; u.pm = pm; u.pn = pn; u.g = 0; u.nt = nt; u.k0 = 0; u.part = -1; return true; }
; #define PG8_STAGE(bufoff, gbase, voff) do { _Pragma("unroll") for (int _i = 0; _i < 2; ++_i) \
;         __builtin_amdgcn_global_load_lds((const unsigned*)((const char*)(gbase) + (voff)[_i]), (LAS unsigned*)(lds + (bufoff) + ldsw + _i * 8192), 16, 0, 0); } while (0)
; #define PG8_WAIT_V(n) asm volatile("s_waitcnt vmcnt(" #n ")" ::: "memory")
; template <class Epi, class Sched>
; __device__ __forceinline__ void gemm_phase(LAS unsigned char* lds, const Gemm g, const Sched& S, const Epi& E) {
;     const int tid = threadIdx.x, wid = __builtin_amdgcn_readfirstlane(tid >> 6), lane = tid & 63, wr = wid >> 2, wc = wid & 3, fr = lane & 15, fq = lane >> 4;
;     unsigned voffA[2], voffB[2];
; #pragma unroll
;     for (int i = 0; i < 2; ++i) { int R, C; stage_rc(tid * 16 + i * 8192, R, C); const int Rb = Epi::PERM ? ((R & ~31) + perm32(R & 31)) : R;
;         voffA[i] = (unsigned)(R * g.lda + C) * 2u; voffB[i] = (unsigned)(Rb * g.ldb + C) * 2u; }
;     const size_t kstep = (size_t)(BK * 2);
;     const size_t hstepA = (size_t)HALF * g.lda * 2, hstepB = (size_t)HALF * g.ldb * 2;
;     const unsigned ldsw = (unsigned)wid * 1024u;
;     const int aoff = lds_byte(wr * 64 + fr, fq * 8), boff = lds_byte(wc * 32 + fr, fq * 8);
;     ...
;     Unit cur, nxt; int ui = 0;
;     if (!S.next(0, cur)) return;
;     f32x4 acc[2][2][4][2];
; #pragma unroll
;     for (int a = 0; a < 2; ++a)
; #pragma unroll
;         for (int b = 0; b < 2; ++b)
; #pragma unroll
;             for (int m = 0; m < 4; ++m)
; #pragma unroll
;                 for (int n = 0; n < 2; ++n) acc[a][b][m][n] = (f32x4){0.f, 0.f, 0.f, 0.f};
;     bf16x8 At[4][2], B0[2][2], B1[2][2];
;     const char* cA = PG8_ABASE(cur); const char* cB = PG8_BBASE(cur);
;     PG8_STAGE(PG8_SB(0, 0), cB, voffB); PG8_STAGE(PG8_SB(0, 1), cB + hstepB, voffB); PG8_STAGE(PG8_SA(0, 0), cA, voffA); PG8_STAGE(PG8_SA(0, 1), cA + hstepA, voffA);
;     if (wr == 1) PG8_BAR;
;     PG8_WAIT_V(2); PG8_BAR;
;     PG8_STAGE(PG8_SB(1, 0), cB + kstep, voffB); PG8_STAGE(PG8_SA(1, 0), cA + kstep, voffA); PG8_STAGE(PG8_SB(1, 1), cB + hstepB + kstep, voffB);
;     PG8_WAIT_V(6); PG8_BAR;
.LBB0_905:
	s_andn2_b64 vcc, exec, s[6:7]
	s_cbranch_vccnz .LBB0_953
	v_lshrrev_b32_e32 v2, 1, v136
	v_lshrrev_b32_e32 v3, 5, v136
	v_and_b32_e32 v2, 24, v2
	v_and_b32_e32 v3, 4, v3
	v_bfe_u32 v4, v136, 2, 2
	v_lshlrev_b32_e32 v0, 4, v136
	s_waitcnt lgkmcnt(0)
	v_and_b32_e32 v1, 32, v136
	v_bfe_u32 v10, v136, 2, 4
	v_or3_b32 v2, v3, v4, v2
	v_lshrrev_b32_e32 v3, 3, v136
	s_movk_i32 s6, 0x70
	v_bitop3_b32 v8, v0, v1, 48 bitop3:0x6c
	v_and_b32_e32 v9, 64, v136
	v_and_or_b32 v4, v3, s6, v10
	s_movk_i32 s6, 0x60
	v_add_u32_e32 v11, 0x2000, v0
	v_or_b32_e32 v1, v8, v9
	v_and_or_b32 v3, v3, s6, v2
	v_lshrrev_b32_e32 v0, 7, v11
	s_movk_i32 s6, 0xf0
	v_lshl_or_b32 v156, v3, 14, v1
	v_and_or_b32 v3, v0, s6, v10
	s_movk_i32 s6, 0xe0
	v_and_or_b32 v0, v0, s6, v2
	s_lshr_b32 s6, s2, 6
	s_ashr_i32 s19, s18, 31
	s_lshr_b32 s5, s2, 8
	s_lshl_b32 s39, s6, 10
	s_lshl_b64 s[8:9], s[18:19], 22
	v_readlane_b32 s20, v242, 6
	v_readlane_b32 s21, v242, 7
	s_add_u32 s7, s20, s8
	s_addc_u32 s13, s21, s9
	s_ashr_i32 s17, s16, 31
	s_lshl_b64 s[8:9], s[16:17], 22
	s_add_u32 s8, s90, s8
	s_addc_u32 s9, s91, s9
	s_add_u32 s66, s8, s0
	s_addc_u32 s67, s9, s1
	s_add_i32 s17, s39, 0
	s_add_i32 m0, s17, 0x10000
	v_lshl_or_b32 v160, v0, 14, v1
	global_load_lds_dwordx4 v156, s[66:67]
	s_add_i32 m0, s17, 0x12000
	s_add_u32 s8, s66, 0x200000
	global_load_lds_dwordx4 v160, s[66:67]
	s_addc_u32 s9, s67, 0
	s_add_i32 m0, s17, 0x14000
	v_lshl_or_b32 v154, v4, 14, v1
	v_and_b32_e32 v240, 0x1c0000, v154
	v_and_b32_e32 v241, 64, v154
	v_lshl_or_b32 v240, v241, 4, v240
	v_and_b32_e32 v241, 63, v136
	v_lshl_or_b32 v154, v241, 4, v240
	global_load_lds_dwordx4 v156, s[8:9]
	s_add_i32 m0, s17, 0x16000
	v_lshl_or_b32 v158, v3, 14, v1
	v_and_b32_e32 v240, 0x1c0000, v158
	v_and_b32_e32 v241, 64, v158
	v_lshl_or_b32 v240, v241, 4, v240
	v_and_b32_e32 v241, 63, v136
	v_lshl_or_b32 v158, v241, 4, v240
	global_load_lds_dwordx4 v160, s[8:9]
	s_lshl_b64 s[100:101], s[0:1], 4
	s_add_u32 s8, s7, s100
	s_addc_u32 s9, s13, s101
	s_add_i32 s72, s17, 0x2000
	s_mov_b32 m0, s17
	s_add_u32 s0, s8, 0x200000
	global_load_lds_dwordx4 v154, s[8:9]
	s_mov_b32 m0, s72
	s_addc_u32 s1, s9, 0
	s_add_i32 s73, s17, 0x4000
	global_load_lds_dwordx4 v158, s[8:9]
	s_mov_b32 m0, s73
	s_add_i32 s76, s17, 0x6000
	global_load_lds_dwordx4 v154, s[0:1]
	s_mov_b32 m0, s76
	v_mov_b32_e32 v163, 0
	global_load_lds_dwordx4 v158, s[0:1]
	v_mov_b32_e32 v157, v163
	v_mov_b32_e32 v161, v163
	v_mov_b32_e32 v155, v163
	v_mov_b32_e32 v159, v163
	s_cmp_eq_u32 s5, 1
	s_mov_b32 s75, s87
	s_mov_b32 s13, 0
	v_lshl_add_u64 v[6:7], s[66:67], 0, v[156:157]
	v_lshl_add_u64 v[4:5], s[66:67], 0, v[160:161]
	v_lshl_add_u64 v[0:1], s[8:9], 0, v[154:155]
	s_cselect_b64 s[20:21], -1, 0
	s_cmp_lg_u32 s5, 1
	v_lshl_add_u64 v[2:3], s[8:9], 0, v[158:159]
	s_cbranch_scc1 .LBB0_908
	s_barrier
.LBB0_908:
	s_lshl_b32 s0, s6, 5
	s_and_b32 s19, s0, 0x60
	s_lshl_b32 s7, s5, 13
	s_lshl_b32 s6, s19, 7
	s_add_u32 s22, s30, 0xc8000
	s_addc_u32 s23, s31, 0
	s_add_u32 s77, s30, 0xea000
	s_mov_b64 s[24:25], 0x80
	s_mov_b64 s[98:99], 0x800
	s_addc_u32 s78, s31, 0
	s_add_i32 m0, s17, 0x18000
	v_lshl_add_u64 v[6:7], v[6:7], 0, s[24:25]
	s_waitcnt vmcnt(2)
	s_barrier
	global_load_lds_dwordx4 v[6:7], off
	v_lshl_add_u64 v[4:5], v[4:5], 0, s[24:25]
	s_add_i32 m0, s17, 0x1a000
	s_add_i32 s79, s17, 0x8000
	s_add_i32 s80, s17, 0xa000
	global_load_lds_dwordx4 v[4:5], off
	v_lshl_add_u64 v[0:1], v[0:1], 0, s[98:99]
	s_mov_b32 m0, s79
	s_add_u32 s0, s66, 0x200080
	global_load_lds_dwordx4 v[0:1], off
	v_lshl_add_u64 v[0:1], v[2:3], 0, s[98:99]
	s_mov_b32 m0, s80
	s_addc_u32 s1, s67, 0
	global_load_lds_dwordx4 v[0:1], off
	s_add_i32 m0, s17, 0x1c000
	v_lshl_add_u64 v[0:1], s[0:1], 0, v[156:157]
	global_load_lds_dwordx4 v[0:1], off
	v_lshl_add_u64 v[0:1], s[0:1], 0, v[160:161]
	s_add_i32 m0, s17, 0x1e000
	v_bfe_u32 v2, v136, 4, 2
	global_load_lds_dwordx4 v[0:1], off
	v_and_b32_e32 v1, 15, v136
	v_lshlrev_b32_e32 v3, 4, v2
	v_lshlrev_b32_e32 v5, 2, v136
	v_lshlrev_b32_e32 v6, 6, v136
	s_movk_i32 s0, 0x3c0
	v_lshl_or_b32 v164, s5, 6, v1
	v_lshl_or_b32 v4, v1, 6, v3
	v_and_b32_e32 v5, 32, v5
	v_and_or_b32 v3, v6, s0, v3
	v_or_b32_e32 v1, v2, v1
	v_bitop3_b32 v4, v4, s7, v5 bitop3:0xde
	v_bitop3_b32 v153, s6, v3, v5 bitop3:0xf6
	v_cmp_eq_u32_e64 s[6:7], 0, v1
	v_lshlrev_b32_e32 v1, 11, v136
	v_lshlrev_b32_e32 v0, 3, v2
	v_cmp_eq_u32_e64 s[0:1], 0, v2
	v_and_b32_e32 v1, 0x1c0000, v1
	v_lshlrev_b32_e32 v2, 14, v10
	v_or3_b32 v1, v8, v1, v2
	v_add_u32_e32 v168, v1, v9
	v_and_b32_e32 v240, 0x1c0000, v168
	v_and_b32_e32 v241, 64, v168
	v_lshl_or_b32 v240, v241, 4, v240
	v_and_b32_e32 v241, 63, v136
	v_lshl_or_b32 v168, v241, 4, v240
	v_lshlrev_b32_e32 v1, 7, v11
	s_waitcnt vmcnt(6)
	s_cmpk_lt_u32 s2, 0x100
	v_mov_b32_e32 v165, v163
	v_and_b32_e32 v1, 0x3c0000, v1
	s_cselect_b64 s[36:37], -1, 0
	v_lshlrev_b64 v[166:167], 13, v[164:165]
	v_or_b32_e32 v165, s19, v0
	v_or3_b32 v1, v8, v1, v2
	s_add_i32 s81, 0, 0x10000
	s_add_i32 s82, 0, 0x14000
	v_lshlrev_b32_e32 v162, 2, v0
	s_mov_b32 s42, 0xf0060000
	s_mov_b32 s44, 0xf0100000
	s_mov_b32 s48, 0xf0120000
	s_mov_b32 s50, 0xf0140000
	s_mov_b32 s52, 0xf0160000
	v_mbcnt_lo_u32_b32 v0, -1, 0
	v_mov_b32_e32 v169, v163
	v_add_u32_e32 v170, v1, v9
	v_and_b32_e32 v240, 0x1c0000, v170
	v_and_b32_e32 v241, 64, v170
	v_lshl_or_b32 v240, v241, 4, v240
	v_and_b32_e32 v241, 63, v136
	v_lshl_or_b32 v170, v241, 4, v240
	v_mov_b32_e32 v171, v163
	v_add_u32_e32 v208, s81, v153
	v_add_u32_e32 v209, s82, v153
	v_and_b32_e32 v210, 0xffffe000, v4
	v_and_b32_e32 v240, 63, v136
	v_lshl_or_b32 v210, v240, 4, v210
	s_mov_b32 s38, 0x3a000000
	s_mov_b32 s83, 0x800000
	s_lshl_b32 s40, s19, 2
	s_mov_b32 s84, 0xf0040000
	s_mov_b32 s43, -1
	s_mov_b32 s85, 0xf0060000
	s_mov_b32 s45, -1
	s_mov_b32 s86, 0xf0100000
	s_mov_b32 s49, -1
	s_mov_b32 s33, 0xf0120000
	s_mov_b32 s51, -1
	s_mov_b32 s53, -1
	v_mbcnt_hi_u32_b32 v211, -1, v0
	s_mov_b32 s87, s13
	s_barrier
	s_branch .LBB0_911
